# k4
# speedup vs baseline: 1.0249x; 1.0249x over previous
; #define DECODE(t_, z_, pm_, pn_) do { if constexpr (EPI == E_CHDFT) { z_ = (t_) >> 5; pm_ = ((t_) >> 4) & 1; pn_ = (int)sx * 16 + ((t_) & 15); break; } \
;     int wgid = (int)sx * tq + (t_); \
;     z_ = wgid / per; int id = wgid % per; \
;     int nig = WGM * nN, gid = id / nig, fm = gid * WGM, gsz = min(nM - fm, WGM); \
;     pm_ = fm + ((id % nig) % gsz); pn_ = (id % nig) / gsz; } while (0)
; #define STAGE_A(Ak_, b, h) do { const char* _s = (Ak_) + (h) * sHA; \
;     glds16(lds0 + ((b) * 2 + (h)) * (HT * 2), voffA, _s); glds16(lds0 + ((b) * 2 + (h)) * (HT * 2) + 8192, voffA, _s + s2A); } while (0)
; #define STAGE_B(Bk_, Bkh_, vh_, b, h) do { const char* _s = (h) ? (Bkh_) : (Bk_); const unsigned _v0 = (h) ? (vh_)[0] : voffB, _v1 = (h) ? (vh_)[1] : voffB; const long _d = (h) ? s2Bh : s2B; \
;     glds16(lds0 + (4 + (b) * 2 + (h)) * (HT * 2), _v0, _s); glds16(lds0 + (4 + (b) * 2 + (h)) * (HT * 2) + 8192, _v1, _s + _d); } while (0)
; #define BAR __builtin_amdgcn_s_barrier()
; template <int EPI>
; __device__ __forceinline__ void gemm_phase(const GemmDesc d, u16* shm, unsigned sx, unsigned srank, unsigned snloc) {
;     ...
;       f32x4 acc[2][2][4][2] = {};
;       bf16x8 At[4][2], B0[2][2], B1[2][2];
;       const int tn = t + (int)snloc;
;       const bool has_next = tn < tq;
;       int zn = z, pmn = pm, pnn = pn; const char *Aun = Au, *Bun = Bu, *Bunh = Buh; unsigned voffBhn[2] = {voffBh[0], voffBh[1]};
;       if (has_next) { DECODE(tn, zn, pmn, pnn); BASES(zn, pmn, pnn, Aun, Bun, Bunh, voffBhn); }
; #pragma unroll 1
;       for (int kt = 0; kt < nt; kt += 2) {
;         const bool lastk = (kt + 2 >= nt);
;         const char* A1 = Au + (long)(kt + 1) * sKA;
;         const char* A2 = lastk ? Aun : Au + (long)(kt + 2) * sKA;
;         const char* B2 = lastk ? Bun : Bu + (long)(kt + 2) * sKB;
;         const char* B2h = lastk ? Bunh : Buh + (long)(kt + 2) * sKB;
;         const unsigned vh[2] = {lastk ? voffBhn[0] : voffBh[0], lastk ? voffBhn[1] : voffBh[1]};
;         const char* A3 = A2 + sKA; const char* B3 = B2 + sKB; const char* B3h = B2h + sKB;
;         LDB(B0, 0, 0); SCHED; LDA(At, 0, 0); STAGE_A(A1, 1, 1);
;         WAIT_L(8); BAR; MMA(0, 0, At, B0); BAR; SCHED;
;         LDB(B1, 0, 1); STAGE_B(B2, B2h, vh, 0, 0);
;         BAR; MMA(0, 1, At, B1); BAR;
;         LDA(At, 0, 1); STAGE_A(A2, 0, 0);
;         BAR; MMA(1, 0, At, B0); BAR; SCHED;
.LBB0_1446:
	s_add_u32 s34, s34, 0x40080
	s_addc_u32 s35, s35, 0
	s_add_u32 s90, s38, 0x100
	s_addc_u32 s91, s39, 0
	s_add_u32 s92, s4, 0x100
	s_addc_u32 s93, s5, 0
	s_mov_b32 s20, 0
.LBB0_1447:
	s_add_i32 s21, s20, 2
	s_add_u32 s0, s34, 0xfffc0080
	s_addc_u32 s1, s35, -1
	s_cmp_lt_u32 s20, 14
	s_cselect_b32 s94, s90, s16
	s_cselect_b32 s51, s1, s15
	s_cselect_b32 s50, s0, s14
	s_cselect_b32 s95, s91, s17
	s_cselect_b32 s47, s93, s25
	s_cselect_b32 s46, s92, s24
	s_add_u32 s40, s94, 0x80
	s_addc_u32 s41, s95, 0
	s_add_u32 s22, s50, 0x80
	s_addc_u32 s23, s51, 0
	s_add_u32 s96, s34, 0x20000
	s_addc_u32 s97, s35, 0
	s_add_u32 s0, s94, 0x20000
	s_addc_u32 s1, s95, 0
	s_add_u32 s52, s50, 0x20000
	s_addc_u32 s53, s51, 0
	s_add_u32 s48, s46, 0x20000
	s_addc_u32 s49, s47, 0
	s_add_u32 s44, s50, 0x40000
	s_addc_u32 s45, s51, 0
	s_add_u32 s28, s50, 0x60000
	s_addc_u32 s29, s51, 0
	s_add_u32 s42, s94, 0x20080
	s_addc_u32 s43, s95, 0
	s_add_u32 s30, s50, 0x20080
	s_addc_u32 s31, s51, 0
	s_add_u32 s18, s46, 0x80
	s_addc_u32 s19, s47, 0
	s_add_u32 s4, s46, 0x20080
	s_addc_u32 s5, s47, 0
	s_add_u32 s38, s34, 0x100
	s_addc_u32 s39, s35, 0
	s_add_u32 s90, s90, 0x100
	s_addc_u32 s91, s91, 0
	s_add_u32 s92, s92, 0x100
	s_addc_u32 s93, s93, 0
	ds_read_b128 v[140:143], v131
	ds_read_b128 v[144:147], v131 offset:1024
	ds_read_b128 v[148:151], v131 offset:2048
	ds_read_b128 v[152:155], v131 offset:3072
	ds_read_b128 v[156:159], v132
	ds_read_b128 v[160:163], v132 offset:1024
	ds_read_b128 v[164:167], v133
	ds_read_b128 v[168:171], v133 offset:1024
	ds_read_b128 v[172:175], v134
	ds_read_b128 v[178:181], v134 offset:1024
	ds_read_b128 v[190:193], v135
	ds_read_b128 v[194:197], v135 offset:1024
	s_mov_b32 m0, s79
	s_nop 0
	global_load_lds_dwordx4 v130, s[34:35]
	s_mov_b32 m0, s80
	s_nop 0
	global_load_lds_dwordx4 v130, s[96:97]
	s_waitcnt lgkmcnt(8)
	s_barrier
	s_setprio 1
	s_waitcnt lgkmcnt(7)
	v_mfma_f32_16x16x32_bf16 v[124:127], v[156:159], v[140:143], 0
	v_mfma_f32_16x16x32_bf16 v[116:119], v[156:159], v[148:151], 0
	s_waitcnt lgkmcnt(5)
	v_mfma_f32_16x16x32_bf16 v[108:111], v[164:167], v[140:143], 0
	v_mfma_f32_16x16x32_bf16 v[100:103], v[164:167], v[148:151], 0
	s_waitcnt lgkmcnt(3)
	v_mfma_f32_16x16x32_bf16 v[92:95], v[172:175], v[140:143], 0
	v_mfma_f32_16x16x32_bf16 v[84:87], v[172:175], v[148:151], 0
	s_waitcnt lgkmcnt(1)
	v_mfma_f32_16x16x32_bf16 v[76:79], v[190:193], v[140:143], 0
	v_mfma_f32_16x16x32_bf16 v[68:71], v[190:193], v[148:151], 0
	v_mfma_f32_16x16x32_bf16 v[124:127], v[160:163], v[144:147], v[124:127]
	v_mfma_f32_16x16x32_bf16 v[116:119], v[160:163], v[152:155], v[116:119]
	v_mfma_f32_16x16x32_bf16 v[108:111], v[168:171], v[144:147], v[108:111]
	v_mfma_f32_16x16x32_bf16 v[100:103], v[168:171], v[152:155], v[100:103]
	v_mfma_f32_16x16x32_bf16 v[92:95], v[178:181], v[144:147], v[92:95]
	v_mfma_f32_16x16x32_bf16 v[84:87], v[178:181], v[152:155], v[84:87]
	s_waitcnt lgkmcnt(0)
	v_mfma_f32_16x16x32_bf16 v[76:79], v[194:197], v[144:147], v[76:79]
	v_mfma_f32_16x16x32_bf16 v[68:71], v[194:197], v[152:155], v[68:71]
	s_setprio 0
	s_barrier
	ds_read_b128 v[198:201], v136
	ds_read_b128 v[202:205], v136 offset:1024
	ds_read_b128 v[206:209], v136 offset:2048
	ds_read_b128 v[210:213], v136 offset:3072
	s_mov_b32 m0, s62
	s_nop 0
	global_load_lds_dwordx4 v130, s[94:95]
	s_mov_b32 m0, s63
	s_nop 0
	global_load_lds_dwordx4 v130, s[0:1]
	s_barrier
	s_setprio 1
	s_waitcnt lgkmcnt(3)
	v_mfma_f32_16x16x32_bf16 v[120:123], v[156:159], v[198:201], 0
	s_waitcnt lgkmcnt(1)
	v_mfma_f32_16x16x32_bf16 v[112:115], v[156:159], v[206:209], 0
	v_mfma_f32_16x16x32_bf16 v[104:107], v[164:167], v[198:201], 0
	v_mfma_f32_16x16x32_bf16 v[96:99], v[164:167], v[206:209], 0
	v_mfma_f32_16x16x32_bf16 v[88:91], v[172:175], v[198:201], 0
	v_mfma_f32_16x16x32_bf16 v[80:83], v[172:175], v[206:209], 0
	v_mfma_f32_16x16x32_bf16 v[72:75], v[190:193], v[198:201], 0
	v_mfma_f32_16x16x32_bf16 v[64:67], v[190:193], v[206:209], 0
	v_mfma_f32_16x16x32_bf16 v[120:123], v[160:163], v[202:205], v[120:123]
	s_waitcnt lgkmcnt(0)
	v_mfma_f32_16x16x32_bf16 v[112:115], v[160:163], v[210:213], v[112:115]
	v_mfma_f32_16x16x32_bf16 v[104:107], v[168:171], v[202:205], v[104:107]
	v_mfma_f32_16x16x32_bf16 v[96:99], v[168:171], v[210:213], v[96:99]
	v_mfma_f32_16x16x32_bf16 v[88:91], v[178:181], v[202:205], v[88:91]
	v_mfma_f32_16x16x32_bf16 v[80:83], v[178:181], v[210:213], v[80:83]
	v_mfma_f32_16x16x32_bf16 v[72:75], v[194:197], v[202:205], v[72:75]
	v_mfma_f32_16x16x32_bf16 v[64:67], v[194:197], v[210:213], v[64:67]
	s_setprio 0
	s_barrier
	ds_read_b128 v[156:159], v132 offset:16384
	ds_read_b128 v[160:163], v132 offset:17408
	ds_read_b128 v[164:167], v133 offset:16384
	ds_read_b128 v[168:171], v133 offset:17408
	ds_read_b128 v[172:175], v134 offset:16384
	ds_read_b128 v[178:181], v134 offset:17408
	ds_read_b128 v[190:193], v135 offset:16384
	ds_read_b128 v[194:197], v135 offset:17408
	s_mov_b32 m0, s59
	s_nop 0
	global_load_lds_dwordx4 v130, s[50:51]
	s_mov_b32 m0, s64
	s_nop 0
	global_load_lds_dwordx4 v130, s[52:53]
	s_barrier
; #define STAGE_A(Ak_, b, h) do { const char* _s = (Ak_) + (h) * sHA; \
;     glds16(lds0 + ((b) * 2 + (h)) * (HT * 2), voffA, _s); glds16(lds0 + ((b) * 2 + (h)) * (HT * 2) + 8192, voffA, _s + s2A); } while (0)
; #define STAGE_B(Bk_, Bkh_, vh_, b, h) do { const char* _s = (h) ? (Bkh_) : (Bk_); const unsigned _v0 = (h) ? (vh_)[0] : voffB, _v1 = (h) ? (vh_)[1] : voffB; const long _d = (h) ? s2Bh : s2B; \
;     glds16(lds0 + (4 + (b) * 2 + (h)) * (HT * 2), _v0, _s); glds16(lds0 + (4 + (b) * 2 + (h)) * (HT * 2) + 8192, _v1, _s + _d); } while (0)
; #define LDA(dst, b, h) for (int m = 0; m < 4; ++m) for (int k = 0; k < 2; ++k) \
;     dst[m][k] = *reinterpret_cast<const bf16x8*>((char*)SA(b, h) + lds_byte(wr * 64 + m * 16 + fr, k * 32 + fq * 8))
; #define LDB(dst, b, h) for (int n = 0; n < 2; ++n) for (int k = 0; k < 2; ++k) \
;     dst[n][k] = *reinterpret_cast<const bf16x8*>((char*)SB(b, h) + lds_byte(wc * 32 + n * 16 + fr, k * 32 + fq * 8))
; #define MMA(ai, bj, At_, Bt_) do { __builtin_amdgcn_s_setprio(1); \
;     for (int m = 0; m < 4; ++m) for (int n = 0; n < 2; ++n) for (int k = 0; k < 2; ++k) \
;       acc[ai][bj][m][n] = __builtin_amdgcn_mfma_f32_16x16x32_bf16(At_[m][k], Bt_[n][k], acc[ai][bj][m][n], 0, 0, 0); \
;     __builtin_amdgcn_s_setprio(0); } while (0)
; #define WAIT_V(n) asm volatile("s_waitcnt vmcnt(" #n ")" ::: "memory")
; #define WAIT_L(n) asm volatile("s_waitcnt lgkmcnt(" #n ")" ::: "memory")
; #define BAR __builtin_amdgcn_s_barrier()
; #define SCHED __builtin_amdgcn_sched_barrier(0)
; template <int EPI>
; __device__ __forceinline__ void gemm_phase(const GemmDesc d, u16* shm, unsigned sx, unsigned srank, unsigned snloc) {
;     ...
;         BAR; MMA(1, 0, At, B0); BAR; SCHED;
;         STAGE_B(B2, B2h, vh, 0, 1);
;         WAIT_V(6); BAR; MMA(1, 1, At, B1); BAR;
;         LDB(B0, 1, 0); SCHED; LDA(At, 1, 0); STAGE_A(A2, 0, 1);
;         WAIT_L(8); BAR; MMA(0, 0, At, B0); BAR; SCHED;
;         LDB(B1, 1, 1); STAGE_B(B3, B3h, vh, 1, 0);
;         BAR; MMA(0, 1, At, B1); BAR;
;         LDA(At, 1, 1); STAGE_A(A3, 1, 0);
;         BAR; MMA(1, 0, At, B0); BAR; SCHED;
	s_setprio 1
	s_waitcnt lgkmcnt(7)
	v_mfma_f32_16x16x32_bf16 v[60:63], v[156:159], v[140:143], 0
	v_mfma_f32_16x16x32_bf16 v[52:55], v[156:159], v[148:151], 0
	s_waitcnt lgkmcnt(5)
	v_mfma_f32_16x16x32_bf16 v[44:47], v[164:167], v[140:143], 0
	v_mfma_f32_16x16x32_bf16 v[36:39], v[164:167], v[148:151], 0
	s_waitcnt lgkmcnt(3)
	v_mfma_f32_16x16x32_bf16 v[28:31], v[172:175], v[140:143], 0
	v_mfma_f32_16x16x32_bf16 v[20:23], v[172:175], v[148:151], 0
	s_waitcnt lgkmcnt(1)
	v_mfma_f32_16x16x32_bf16 v[12:15], v[190:193], v[140:143], 0
	v_mfma_f32_16x16x32_bf16 v[4:7], v[190:193], v[148:151], 0
	v_mfma_f32_16x16x32_bf16 v[60:63], v[160:163], v[144:147], v[60:63]
	v_mfma_f32_16x16x32_bf16 v[52:55], v[160:163], v[152:155], v[52:55]
	v_mfma_f32_16x16x32_bf16 v[44:47], v[168:171], v[144:147], v[44:47]
	v_mfma_f32_16x16x32_bf16 v[36:39], v[168:171], v[152:155], v[36:39]
	v_mfma_f32_16x16x32_bf16 v[28:31], v[178:181], v[144:147], v[28:31]
	v_mfma_f32_16x16x32_bf16 v[20:23], v[178:181], v[152:155], v[20:23]
	s_waitcnt lgkmcnt(0)
	v_mfma_f32_16x16x32_bf16 v[12:15], v[194:197], v[144:147], v[12:15]
	v_mfma_f32_16x16x32_bf16 v[4:7], v[194:197], v[152:155], v[4:7]
	s_setprio 0
	s_barrier
	s_mov_b32 m0, s65
	s_nop 0
	global_load_lds_dwordx4 v130, s[46:47]
	s_mov_b32 m0, s66
	s_nop 0
	global_load_lds_dwordx4 v130, s[48:49]
	s_waitcnt vmcnt(6)
	s_barrier
	s_setprio 1
	v_mfma_f32_16x16x32_bf16 v[56:59], v[156:159], v[198:201], 0
	v_mfma_f32_16x16x32_bf16 v[48:51], v[156:159], v[206:209], 0
	v_mfma_f32_16x16x32_bf16 v[40:43], v[164:167], v[198:201], 0
	v_mfma_f32_16x16x32_bf16 v[32:35], v[164:167], v[206:209], 0
	v_mfma_f32_16x16x32_bf16 v[24:27], v[172:175], v[198:201], 0
	v_mfma_f32_16x16x32_bf16 v[16:19], v[172:175], v[206:209], 0
	v_mfma_f32_16x16x32_bf16 v[8:11], v[190:193], v[198:201], 0
	v_mfma_f32_16x16x32_bf16 v[0:3], v[190:193], v[206:209], 0
	v_mfma_f32_16x16x32_bf16 v[56:59], v[160:163], v[202:205], v[56:59]
	v_mfma_f32_16x16x32_bf16 v[48:51], v[160:163], v[210:213], v[48:51]
	v_mfma_f32_16x16x32_bf16 v[40:43], v[168:171], v[202:205], v[40:43]
	v_mfma_f32_16x16x32_bf16 v[32:35], v[168:171], v[210:213], v[32:35]
	v_mfma_f32_16x16x32_bf16 v[24:27], v[178:181], v[202:205], v[24:27]
	v_mfma_f32_16x16x32_bf16 v[16:19], v[178:181], v[210:213], v[16:19]
	v_mfma_f32_16x16x32_bf16 v[8:11], v[194:197], v[202:205], v[8:11]
	v_mfma_f32_16x16x32_bf16 v[0:3], v[194:197], v[210:213], v[0:3]
	s_setprio 0
	s_barrier
	ds_read_b128 v[140:143], v137
	ds_read_b128 v[144:147], v137 offset:1024
	ds_read_b128 v[148:151], v137 offset:2048
	ds_read_b128 v[152:155], v137 offset:3072
	ds_read_b128 v[156:159], v132 offset:32768
	ds_read_b128 v[160:163], v132 offset:33792
	ds_read_b128 v[164:167], v133 offset:32768
	ds_read_b128 v[168:171], v133 offset:33792
	ds_read_b128 v[172:175], v134 offset:32768
	ds_read_b128 v[178:181], v134 offset:33792
	ds_read_b128 v[190:193], v135 offset:32768
	ds_read_b128 v[194:197], v135 offset:33792
	s_mov_b32 m0, s67
	s_nop 0
	global_load_lds_dwordx4 v130, s[44:45]
	s_mov_b32 m0, s69
	s_nop 0
	global_load_lds_dwordx4 v130, s[28:29]
	s_waitcnt lgkmcnt(8)
	s_barrier
	s_setprio 1
	s_waitcnt lgkmcnt(7)
	v_mfma_f32_16x16x32_bf16 v[124:127], v[156:159], v[140:143], v[124:127]
	v_mfma_f32_16x16x32_bf16 v[116:119], v[156:159], v[148:151], v[116:119]
	s_waitcnt lgkmcnt(5)
	v_mfma_f32_16x16x32_bf16 v[108:111], v[164:167], v[140:143], v[108:111]
	v_mfma_f32_16x16x32_bf16 v[100:103], v[164:167], v[148:151], v[100:103]
	s_waitcnt lgkmcnt(3)
	v_mfma_f32_16x16x32_bf16 v[92:95], v[172:175], v[140:143], v[92:95]
	v_mfma_f32_16x16x32_bf16 v[84:87], v[172:175], v[148:151], v[84:87]
	s_waitcnt lgkmcnt(1)
	v_mfma_f32_16x16x32_bf16 v[76:79], v[190:193], v[140:143], v[76:79]
	v_mfma_f32_16x16x32_bf16 v[68:71], v[190:193], v[148:151], v[68:71]
	v_mfma_f32_16x16x32_bf16 v[124:127], v[160:163], v[144:147], v[124:127]
	v_mfma_f32_16x16x32_bf16 v[116:119], v[160:163], v[152:155], v[116:119]
	v_mfma_f32_16x16x32_bf16 v[108:111], v[168:171], v[144:147], v[108:111]
	v_mfma_f32_16x16x32_bf16 v[100:103], v[168:171], v[152:155], v[100:103]
	v_mfma_f32_16x16x32_bf16 v[92:95], v[178:181], v[144:147], v[92:95]
	v_mfma_f32_16x16x32_bf16 v[84:87], v[178:181], v[152:155], v[84:87]
	s_waitcnt lgkmcnt(0)
	v_mfma_f32_16x16x32_bf16 v[76:79], v[194:197], v[144:147], v[76:79]
	v_mfma_f32_16x16x32_bf16 v[68:71], v[194:197], v[152:155], v[68:71]
	s_setprio 0
	s_barrier
	ds_read_b128 v[198:201], v138
	ds_read_b128 v[202:205], v138 offset:1024
	ds_read_b128 v[206:209], v138 offset:2048
	ds_read_b128 v[210:213], v138 offset:3072
	s_mov_b32 m0, s71
	s_nop 0
	global_load_lds_dwordx4 v130, s[40:41]
	s_mov_b32 m0, s72
	s_nop 0
	global_load_lds_dwordx4 v130, s[42:43]
	s_barrier
	s_setprio 1
	s_waitcnt lgkmcnt(3)
	v_mfma_f32_16x16x32_bf16 v[120:123], v[156:159], v[198:201], v[120:123]
	s_waitcnt lgkmcnt(1)
	v_mfma_f32_16x16x32_bf16 v[112:115], v[156:159], v[206:209], v[112:115]
	v_mfma_f32_16x16x32_bf16 v[104:107], v[164:167], v[198:201], v[104:107]
	v_mfma_f32_16x16x32_bf16 v[96:99], v[164:167], v[206:209], v[96:99]
	v_mfma_f32_16x16x32_bf16 v[88:91], v[172:175], v[198:201], v[88:91]
	v_mfma_f32_16x16x32_bf16 v[80:83], v[172:175], v[206:209], v[80:83]
	v_mfma_f32_16x16x32_bf16 v[72:75], v[190:193], v[198:201], v[72:75]
	v_mfma_f32_16x16x32_bf16 v[64:67], v[190:193], v[206:209], v[64:67]
	v_mfma_f32_16x16x32_bf16 v[120:123], v[160:163], v[202:205], v[120:123]
	s_waitcnt lgkmcnt(0)
	v_mfma_f32_16x16x32_bf16 v[112:115], v[160:163], v[210:213], v[112:115]
	v_mfma_f32_16x16x32_bf16 v[104:107], v[168:171], v[202:205], v[104:107]
	v_mfma_f32_16x16x32_bf16 v[96:99], v[168:171], v[210:213], v[96:99]
	v_mfma_f32_16x16x32_bf16 v[88:91], v[178:181], v[202:205], v[88:91]
	v_mfma_f32_16x16x32_bf16 v[80:83], v[178:181], v[210:213], v[80:83]
	v_mfma_f32_16x16x32_bf16 v[72:75], v[194:197], v[202:205], v[72:75]
	v_mfma_f32_16x16x32_bf16 v[64:67], v[194:197], v[210:213], v[64:67]
	s_setprio 0
	s_barrier
; #define STAGE_A(Ak_, b, h) do { const char* _s = (Ak_) + (h) * sHA; \
;     glds16(lds0 + ((b) * 2 + (h)) * (HT * 2), voffA, _s); glds16(lds0 + ((b) * 2 + (h)) * (HT * 2) + 8192, voffA, _s + s2A); } while (0)
; #define STAGE_B(Bk_, Bkh_, vh_, b, h) do { const char* _s = (h) ? (Bkh_) : (Bk_); const unsigned _v0 = (h) ? (vh_)[0] : voffB, _v1 = (h) ? (vh_)[1] : voffB; const long _d = (h) ? s2Bh : s2B; \
;     glds16(lds0 + (4 + (b) * 2 + (h)) * (HT * 2), _v0, _s); glds16(lds0 + (4 + (b) * 2 + (h)) * (HT * 2) + 8192, _v1, _s + _d); } while (0)
; #define LDA(dst, b, h) for (int m = 0; m < 4; ++m) for (int k = 0; k < 2; ++k) \
;     dst[m][k] = *reinterpret_cast<const bf16x8*>((char*)SA(b, h) + lds_byte(wr * 64 + m * 16 + fr, k * 32 + fq * 8))
; #define LDB(dst, b, h) for (int n = 0; n < 2; ++n) for (int k = 0; k < 2; ++k) \
;     dst[n][k] = *reinterpret_cast<const bf16x8*>((char*)SB(b, h) + lds_byte(wc * 32 + n * 16 + fr, k * 32 + fq * 8))
; #define WAIT_V(n) asm volatile("s_waitcnt vmcnt(" #n ")" ::: "memory")
; #define WAIT_L(n) asm volatile("s_waitcnt lgkmcnt(" #n ")" ::: "memory")
; #define BAR __builtin_amdgcn_s_barrier()
; template <int EPI>
; __device__ __forceinline__ void gemm_phase(const GemmDesc d, u16* shm, unsigned sx, unsigned srank, unsigned snloc) {
;     ...
;       for (int kt = 0; kt < nt; kt += 2) {
;         const bool lastk = (kt + 2 >= nt);
;         const char* A1 = Au + (long)(kt + 1) * sKA;
;         const char* A2 = lastk ? Aun : Au + (long)(kt + 2) * sKA;
;         const char* B2 = lastk ? Bun : Bu + (long)(kt + 2) * sKB;
;         const char* B2h = lastk ? Bunh : Buh + (long)(kt + 2) * sKB;
;         const unsigned vh[2] = {lastk ? voffBhn[0] : voffBh[0], lastk ? voffBhn[1] : voffBh[1]};
;         const char* A3 = A2 + sKA; const char* B3 = B2 + sKB; const char* B3h = B2h + sKB;
;         LDB(B0, 0, 0); SCHED; LDA(At, 0, 0); STAGE_A(A1, 1, 1);
;         WAIT_L(8); BAR; MMA(0, 0, At, B0); BAR; SCHED;
;     ...
;         WAIT_V(6); BAR; MMA(1, 1, At, B1); BAR;
;         LDB(B0, 1, 0); SCHED; LDA(At, 1, 0); STAGE_A(A2, 0, 1);
;         WAIT_L(8); BAR; MMA(0, 0, At, B0); BAR; SCHED;
;         LDB(B1, 1, 1); STAGE_B(B3, B3h, vh, 1, 0);
;         BAR; MMA(0, 1, At, B1); BAR;
;         LDA(At, 1, 1); STAGE_A(A3, 1, 0);
;         BAR; MMA(1, 0, At, B0); BAR; SCHED;
;         STAGE_B(B3, B3h, vh, 1, 1);
;         WAIT_V(6); BAR; MMA(1, 1, At, B1); BAR;
	ds_read_b128 v[156:159], v132 offset:49152
	ds_read_b128 v[160:163], v132 offset:50176
	ds_read_b128 v[164:167], v133 offset:49152
	ds_read_b128 v[168:171], v133 offset:50176
	ds_read_b128 v[172:175], v134 offset:49152
	ds_read_b128 v[178:181], v134 offset:50176
	ds_read_b128 v[190:193], v135 offset:49152
	ds_read_b128 v[194:197], v135 offset:50176
	s_mov_b32 m0, s73
	s_nop 0
	global_load_lds_dwordx4 v130, s[22:23]
	s_mov_b32 m0, s76
	s_nop 0
	global_load_lds_dwordx4 v130, s[30:31]
	s_barrier
	s_setprio 1
	s_waitcnt lgkmcnt(7)
	v_mfma_f32_16x16x32_bf16 v[60:63], v[156:159], v[140:143], v[60:63]
	v_mfma_f32_16x16x32_bf16 v[52:55], v[156:159], v[148:151], v[52:55]
	s_waitcnt lgkmcnt(5)
	v_mfma_f32_16x16x32_bf16 v[44:47], v[164:167], v[140:143], v[44:47]
	v_mfma_f32_16x16x32_bf16 v[36:39], v[164:167], v[148:151], v[36:39]
	s_waitcnt lgkmcnt(3)
	v_mfma_f32_16x16x32_bf16 v[28:31], v[172:175], v[140:143], v[28:31]
	v_mfma_f32_16x16x32_bf16 v[20:23], v[172:175], v[148:151], v[20:23]
	s_waitcnt lgkmcnt(1)
	v_mfma_f32_16x16x32_bf16 v[12:15], v[190:193], v[140:143], v[12:15]
	v_mfma_f32_16x16x32_bf16 v[4:7], v[190:193], v[148:151], v[4:7]
	v_mfma_f32_16x16x32_bf16 v[60:63], v[160:163], v[144:147], v[60:63]
	v_mfma_f32_16x16x32_bf16 v[52:55], v[160:163], v[152:155], v[52:55]
	v_mfma_f32_16x16x32_bf16 v[44:47], v[168:171], v[144:147], v[44:47]
	v_mfma_f32_16x16x32_bf16 v[36:39], v[168:171], v[152:155], v[36:39]
	v_mfma_f32_16x16x32_bf16 v[28:31], v[178:181], v[144:147], v[28:31]
	v_mfma_f32_16x16x32_bf16 v[20:23], v[178:181], v[152:155], v[20:23]
	s_waitcnt lgkmcnt(0)
	v_mfma_f32_16x16x32_bf16 v[12:15], v[194:197], v[144:147], v[12:15]
	v_mfma_f32_16x16x32_bf16 v[4:7], v[194:197], v[152:155], v[4:7]
	s_setprio 0
	s_barrier
	s_mov_b32 m0, s77
	s_nop 0
	global_load_lds_dwordx4 v130, s[18:19]
	s_mov_b32 m0, s78
	s_nop 0
	global_load_lds_dwordx4 v130, s[4:5]
	s_mov_b64 s[34:35], s[38:39]
	s_mov_b32 s20, s21
	s_add_i32 s21, s20, 2
	s_add_u32 s0, s34, 0xfffc0080
	s_addc_u32 s1, s35, -1
	s_cmp_lt_u32 s20, 14
	s_cselect_b32 s94, s90, s16
	s_cselect_b32 s51, s1, s15
	s_cselect_b32 s50, s0, s14
	s_cselect_b32 s95, s91, s17
	s_cselect_b32 s47, s93, s25
	s_cselect_b32 s46, s92, s24
	s_add_u32 s40, s94, 0x80
	s_addc_u32 s41, s95, 0
	s_add_u32 s22, s50, 0x80
	s_addc_u32 s23, s51, 0
	s_add_u32 s96, s34, 0x20000
	s_addc_u32 s97, s35, 0
	s_add_u32 s0, s94, 0x20000
	s_addc_u32 s1, s95, 0
	s_add_u32 s52, s50, 0x20000
	s_addc_u32 s53, s51, 0
	s_add_u32 s48, s46, 0x20000
	s_addc_u32 s49, s47, 0
	s_add_u32 s44, s50, 0x40000
	s_addc_u32 s45, s51, 0
	s_add_u32 s28, s50, 0x60000
	s_addc_u32 s29, s51, 0
	s_add_u32 s42, s94, 0x20080
	s_addc_u32 s43, s95, 0
	s_add_u32 s30, s50, 0x20080
	s_addc_u32 s31, s51, 0
	s_add_u32 s18, s46, 0x80
	s_addc_u32 s19, s47, 0
	s_add_u32 s4, s46, 0x20080
	s_addc_u32 s5, s47, 0
	s_add_u32 s38, s34, 0x100
	s_addc_u32 s39, s35, 0
	s_add_u32 s90, s90, 0x100
	s_addc_u32 s91, s91, 0
	s_add_u32 s92, s92, 0x100
	s_addc_u32 s93, s93, 0
	s_waitcnt vmcnt(6)
	s_barrier
	s_setprio 1
	v_mfma_f32_16x16x32_bf16 v[56:59], v[156:159], v[198:201], v[56:59]
	v_mfma_f32_16x16x32_bf16 v[48:51], v[156:159], v[206:209], v[48:51]
	v_mfma_f32_16x16x32_bf16 v[40:43], v[164:167], v[198:201], v[40:43]
	v_mfma_f32_16x16x32_bf16 v[32:35], v[164:167], v[206:209], v[32:35]
	v_mfma_f32_16x16x32_bf16 v[24:27], v[172:175], v[198:201], v[24:27]
	v_mfma_f32_16x16x32_bf16 v[16:19], v[172:175], v[206:209], v[16:19]
	v_mfma_f32_16x16x32_bf16 v[8:11], v[190:193], v[198:201], v[8:11]
	v_mfma_f32_16x16x32_bf16 v[0:3], v[190:193], v[206:209], v[0:3]
	v_mfma_f32_16x16x32_bf16 v[56:59], v[160:163], v[202:205], v[56:59]
	v_mfma_f32_16x16x32_bf16 v[48:51], v[160:163], v[210:213], v[48:51]
	v_mfma_f32_16x16x32_bf16 v[40:43], v[168:171], v[202:205], v[40:43]
	v_mfma_f32_16x16x32_bf16 v[32:35], v[168:171], v[210:213], v[32:35]
	v_mfma_f32_16x16x32_bf16 v[24:27], v[178:181], v[202:205], v[24:27]
	v_mfma_f32_16x16x32_bf16 v[16:19], v[178:181], v[210:213], v[16:19]
	v_mfma_f32_16x16x32_bf16 v[8:11], v[194:197], v[202:205], v[8:11]
	v_mfma_f32_16x16x32_bf16 v[0:3], v[194:197], v[210:213], v[0:3]
	s_setprio 0
	s_barrier
.Lgu_kloop:
	ds_read_b128 v[140:143], v131
	ds_read_b128 v[144:147], v131 offset:1024
	ds_read_b128 v[148:151], v131 offset:2048
	ds_read_b128 v[152:155], v131 offset:3072
	ds_read_b128 v[156:159], v132
	ds_read_b128 v[160:163], v132 offset:1024
	ds_read_b128 v[164:167], v133
	ds_read_b128 v[168:171], v133 offset:1024
	ds_read_b128 v[172:175], v134
	ds_read_b128 v[178:181], v134 offset:1024
	ds_read_b128 v[190:193], v135
	ds_read_b128 v[194:197], v135 offset:1024
	s_mov_b32 m0, s79
	s_nop 0
	global_load_lds_dwordx4 v130, s[34:35]
	s_mov_b32 m0, s80
	s_nop 0
	global_load_lds_dwordx4 v130, s[96:97]
	s_waitcnt lgkmcnt(8)
	s_barrier
	s_setprio 1
	s_waitcnt lgkmcnt(7)
	v_mfma_f32_16x16x32_bf16 v[124:127], v[156:159], v[140:143], v[124:127]
	v_mfma_f32_16x16x32_bf16 v[116:119], v[156:159], v[148:151], v[116:119]
	s_waitcnt lgkmcnt(5)
	v_mfma_f32_16x16x32_bf16 v[108:111], v[164:167], v[140:143], v[108:111]
	v_mfma_f32_16x16x32_bf16 v[100:103], v[164:167], v[148:151], v[100:103]
	s_waitcnt lgkmcnt(3)
	v_mfma_f32_16x16x32_bf16 v[92:95], v[172:175], v[140:143], v[92:95]
	v_mfma_f32_16x16x32_bf16 v[84:87], v[172:175], v[148:151], v[84:87]
	s_waitcnt lgkmcnt(1)
	v_mfma_f32_16x16x32_bf16 v[76:79], v[190:193], v[140:143], v[76:79]
	v_mfma_f32_16x16x32_bf16 v[68:71], v[190:193], v[148:151], v[68:71]
	v_mfma_f32_16x16x32_bf16 v[124:127], v[160:163], v[144:147], v[124:127]
	v_mfma_f32_16x16x32_bf16 v[116:119], v[160:163], v[152:155], v[116:119]
	v_mfma_f32_16x16x32_bf16 v[108:111], v[168:171], v[144:147], v[108:111]
	v_mfma_f32_16x16x32_bf16 v[100:103], v[168:171], v[152:155], v[100:103]
	v_mfma_f32_16x16x32_bf16 v[92:95], v[178:181], v[144:147], v[92:95]
	v_mfma_f32_16x16x32_bf16 v[84:87], v[178:181], v[152:155], v[84:87]
	s_waitcnt lgkmcnt(0)
	v_mfma_f32_16x16x32_bf16 v[76:79], v[194:197], v[144:147], v[76:79]
	v_mfma_f32_16x16x32_bf16 v[68:71], v[194:197], v[152:155], v[68:71]
	s_setprio 0
	s_barrier
; #define STAGE_A(Ak_, b, h) do { const char* _s = (Ak_) + (h) * sHA; \
;     glds16(lds0 + ((b) * 2 + (h)) * (HT * 2), voffA, _s); glds16(lds0 + ((b) * 2 + (h)) * (HT * 2) + 8192, voffA, _s + s2A); } while (0)
; #define STAGE_B(Bk_, Bkh_, vh_, b, h) do { const char* _s = (h) ? (Bkh_) : (Bk_); const unsigned _v0 = (h) ? (vh_)[0] : voffB, _v1 = (h) ? (vh_)[1] : voffB; const long _d = (h) ? s2Bh : s2B; \
;     glds16(lds0 + (4 + (b) * 2 + (h)) * (HT * 2), _v0, _s); glds16(lds0 + (4 + (b) * 2 + (h)) * (HT * 2) + 8192, _v1, _s + _d); } while (0)
; #define LDA(dst, b, h) for (int m = 0; m < 4; ++m) for (int k = 0; k < 2; ++k) \
;     dst[m][k] = *reinterpret_cast<const bf16x8*>((char*)SA(b, h) + lds_byte(wr * 64 + m * 16 + fr, k * 32 + fq * 8))
; #define LDB(dst, b, h) for (int n = 0; n < 2; ++n) for (int k = 0; k < 2; ++k) \
;     dst[n][k] = *reinterpret_cast<const bf16x8*>((char*)SB(b, h) + lds_byte(wc * 32 + n * 16 + fr, k * 32 + fq * 8))
; #define MMA(ai, bj, At_, Bt_) do { __builtin_amdgcn_s_setprio(1); \
;     for (int m = 0; m < 4; ++m) for (int n = 0; n < 2; ++n) for (int k = 0; k < 2; ++k) \
;       acc[ai][bj][m][n] = __builtin_amdgcn_mfma_f32_16x16x32_bf16(At_[m][k], Bt_[n][k], acc[ai][bj][m][n], 0, 0, 0); \
;     __builtin_amdgcn_s_setprio(0); } while (0)
; #define WAIT_V(n) asm volatile("s_waitcnt vmcnt(" #n ")" ::: "memory")
; #define WAIT_L(n) asm volatile("s_waitcnt lgkmcnt(" #n ")" ::: "memory")
; #define BAR __builtin_amdgcn_s_barrier()
; #define SCHED __builtin_amdgcn_sched_barrier(0)
; template <int EPI>
; __device__ __forceinline__ void gemm_phase(const GemmDesc d, u16* shm, unsigned sx, unsigned srank, unsigned snloc) {
;     ...
;         LDB(B1, 0, 1); STAGE_B(B2, B2h, vh, 0, 0);
;         BAR; MMA(0, 1, At, B1); BAR;
;         LDA(At, 0, 1); STAGE_A(A2, 0, 0);
;         BAR; MMA(1, 0, At, B0); BAR; SCHED;
;         STAGE_B(B2, B2h, vh, 0, 1);
;         WAIT_V(6); BAR; MMA(1, 1, At, B1); BAR;
;         LDB(B0, 1, 0); SCHED; LDA(At, 1, 0); STAGE_A(A2, 0, 1);
;         WAIT_L(8); BAR; MMA(0, 0, At, B0); BAR; SCHED;
	ds_read_b128 v[198:201], v136
	ds_read_b128 v[202:205], v136 offset:1024
	ds_read_b128 v[206:209], v136 offset:2048
	ds_read_b128 v[210:213], v136 offset:3072
	s_mov_b32 m0, s62
	s_nop 0
	global_load_lds_dwordx4 v130, s[94:95]
	s_mov_b32 m0, s63
	s_nop 0
	global_load_lds_dwordx4 v130, s[0:1]
	s_barrier
	s_setprio 1
	s_waitcnt lgkmcnt(3)
	v_mfma_f32_16x16x32_bf16 v[120:123], v[156:159], v[198:201], v[120:123]
	s_waitcnt lgkmcnt(1)
	v_mfma_f32_16x16x32_bf16 v[112:115], v[156:159], v[206:209], v[112:115]
	v_mfma_f32_16x16x32_bf16 v[104:107], v[164:167], v[198:201], v[104:107]
	v_mfma_f32_16x16x32_bf16 v[96:99], v[164:167], v[206:209], v[96:99]
	v_mfma_f32_16x16x32_bf16 v[88:91], v[172:175], v[198:201], v[88:91]
	v_mfma_f32_16x16x32_bf16 v[80:83], v[172:175], v[206:209], v[80:83]
	v_mfma_f32_16x16x32_bf16 v[72:75], v[190:193], v[198:201], v[72:75]
	v_mfma_f32_16x16x32_bf16 v[64:67], v[190:193], v[206:209], v[64:67]
	v_mfma_f32_16x16x32_bf16 v[120:123], v[160:163], v[202:205], v[120:123]
	s_waitcnt lgkmcnt(0)
	v_mfma_f32_16x16x32_bf16 v[112:115], v[160:163], v[210:213], v[112:115]
	v_mfma_f32_16x16x32_bf16 v[104:107], v[168:171], v[202:205], v[104:107]
	v_mfma_f32_16x16x32_bf16 v[96:99], v[168:171], v[210:213], v[96:99]
	v_mfma_f32_16x16x32_bf16 v[88:91], v[178:181], v[202:205], v[88:91]
	v_mfma_f32_16x16x32_bf16 v[80:83], v[178:181], v[210:213], v[80:83]
	v_mfma_f32_16x16x32_bf16 v[72:75], v[194:197], v[202:205], v[72:75]
	v_mfma_f32_16x16x32_bf16 v[64:67], v[194:197], v[210:213], v[64:67]
	s_setprio 0
	s_barrier
	ds_read_b128 v[156:159], v132 offset:16384
	ds_read_b128 v[160:163], v132 offset:17408
	ds_read_b128 v[164:167], v133 offset:16384
	ds_read_b128 v[168:171], v133 offset:17408
	ds_read_b128 v[172:175], v134 offset:16384
	ds_read_b128 v[178:181], v134 offset:17408
	ds_read_b128 v[190:193], v135 offset:16384
	ds_read_b128 v[194:197], v135 offset:17408
	s_mov_b32 m0, s59
	s_nop 0
	global_load_lds_dwordx4 v130, s[50:51]
	s_mov_b32 m0, s64
	s_nop 0
	global_load_lds_dwordx4 v130, s[52:53]
	s_barrier
	s_setprio 1
	s_waitcnt lgkmcnt(7)
	v_mfma_f32_16x16x32_bf16 v[60:63], v[156:159], v[140:143], v[60:63]
	v_mfma_f32_16x16x32_bf16 v[52:55], v[156:159], v[148:151], v[52:55]
	s_waitcnt lgkmcnt(5)
	v_mfma_f32_16x16x32_bf16 v[44:47], v[164:167], v[140:143], v[44:47]
	v_mfma_f32_16x16x32_bf16 v[36:39], v[164:167], v[148:151], v[36:39]
	s_waitcnt lgkmcnt(3)
	v_mfma_f32_16x16x32_bf16 v[28:31], v[172:175], v[140:143], v[28:31]
	v_mfma_f32_16x16x32_bf16 v[20:23], v[172:175], v[148:151], v[20:23]
	s_waitcnt lgkmcnt(1)
	v_mfma_f32_16x16x32_bf16 v[12:15], v[190:193], v[140:143], v[12:15]
	v_mfma_f32_16x16x32_bf16 v[4:7], v[190:193], v[148:151], v[4:7]
	v_mfma_f32_16x16x32_bf16 v[60:63], v[160:163], v[144:147], v[60:63]
	v_mfma_f32_16x16x32_bf16 v[52:55], v[160:163], v[152:155], v[52:55]
	v_mfma_f32_16x16x32_bf16 v[44:47], v[168:171], v[144:147], v[44:47]
	v_mfma_f32_16x16x32_bf16 v[36:39], v[168:171], v[152:155], v[36:39]
	v_mfma_f32_16x16x32_bf16 v[28:31], v[178:181], v[144:147], v[28:31]
	v_mfma_f32_16x16x32_bf16 v[20:23], v[178:181], v[152:155], v[20:23]
	s_waitcnt lgkmcnt(0)
	v_mfma_f32_16x16x32_bf16 v[12:15], v[194:197], v[144:147], v[12:15]
	v_mfma_f32_16x16x32_bf16 v[4:7], v[194:197], v[152:155], v[4:7]
	s_setprio 0
	s_barrier
	s_mov_b32 m0, s65
	s_nop 0
	global_load_lds_dwordx4 v130, s[46:47]
	s_mov_b32 m0, s66
	s_nop 0
	global_load_lds_dwordx4 v130, s[48:49]
	s_waitcnt vmcnt(6)
	s_barrier
	s_setprio 1
	v_mfma_f32_16x16x32_bf16 v[56:59], v[156:159], v[198:201], v[56:59]
	v_mfma_f32_16x16x32_bf16 v[48:51], v[156:159], v[206:209], v[48:51]
	v_mfma_f32_16x16x32_bf16 v[40:43], v[164:167], v[198:201], v[40:43]
	v_mfma_f32_16x16x32_bf16 v[32:35], v[164:167], v[206:209], v[32:35]
	v_mfma_f32_16x16x32_bf16 v[24:27], v[172:175], v[198:201], v[24:27]
	v_mfma_f32_16x16x32_bf16 v[16:19], v[172:175], v[206:209], v[16:19]
	v_mfma_f32_16x16x32_bf16 v[8:11], v[190:193], v[198:201], v[8:11]
	v_mfma_f32_16x16x32_bf16 v[0:3], v[190:193], v[206:209], v[0:3]
	v_mfma_f32_16x16x32_bf16 v[56:59], v[160:163], v[202:205], v[56:59]
	v_mfma_f32_16x16x32_bf16 v[48:51], v[160:163], v[210:213], v[48:51]
	v_mfma_f32_16x16x32_bf16 v[40:43], v[168:171], v[202:205], v[40:43]
	v_mfma_f32_16x16x32_bf16 v[32:35], v[168:171], v[210:213], v[32:35]
	v_mfma_f32_16x16x32_bf16 v[24:27], v[178:181], v[202:205], v[24:27]
	v_mfma_f32_16x16x32_bf16 v[16:19], v[178:181], v[210:213], v[16:19]
	v_mfma_f32_16x16x32_bf16 v[8:11], v[194:197], v[202:205], v[8:11]
	v_mfma_f32_16x16x32_bf16 v[0:3], v[194:197], v[210:213], v[0:3]
	s_setprio 0
	s_barrier
	ds_read_b128 v[140:143], v137
	ds_read_b128 v[144:147], v137 offset:1024
	ds_read_b128 v[148:151], v137 offset:2048
	ds_read_b128 v[152:155], v137 offset:3072
	ds_read_b128 v[156:159], v132 offset:32768
	ds_read_b128 v[160:163], v132 offset:33792
	ds_read_b128 v[164:167], v133 offset:32768
	ds_read_b128 v[168:171], v133 offset:33792
	ds_read_b128 v[172:175], v134 offset:32768
	ds_read_b128 v[178:181], v134 offset:33792
	ds_read_b128 v[190:193], v135 offset:32768
	ds_read_b128 v[194:197], v135 offset:33792
	s_mov_b32 m0, s67
	s_nop 0
	global_load_lds_dwordx4 v130, s[44:45]
	s_mov_b32 m0, s69
	s_nop 0
	global_load_lds_dwordx4 v130, s[28:29]
	s_waitcnt lgkmcnt(8)
	s_barrier
; #define STAGE_A(Ak_, b, h) do { const char* _s = (Ak_) + (h) * sHA; \
;     glds16(lds0 + ((b) * 2 + (h)) * (HT * 2), voffA, _s); glds16(lds0 + ((b) * 2 + (h)) * (HT * 2) + 8192, voffA, _s + s2A); } while (0)
; #define STAGE_B(Bk_, Bkh_, vh_, b, h) do { const char* _s = (h) ? (Bkh_) : (Bk_); const unsigned _v0 = (h) ? (vh_)[0] : voffB, _v1 = (h) ? (vh_)[1] : voffB; const long _d = (h) ? s2Bh : s2B; \
;     glds16(lds0 + (4 + (b) * 2 + (h)) * (HT * 2), _v0, _s); glds16(lds0 + (4 + (b) * 2 + (h)) * (HT * 2) + 8192, _v1, _s + _d); } while (0)
; #define LDA(dst, b, h) for (int m = 0; m < 4; ++m) for (int k = 0; k < 2; ++k) \
;     dst[m][k] = *reinterpret_cast<const bf16x8*>((char*)SA(b, h) + lds_byte(wr * 64 + m * 16 + fr, k * 32 + fq * 8))
; #define LDB(dst, b, h) for (int n = 0; n < 2; ++n) for (int k = 0; k < 2; ++k) \
;     dst[n][k] = *reinterpret_cast<const bf16x8*>((char*)SB(b, h) + lds_byte(wc * 32 + n * 16 + fr, k * 32 + fq * 8))
; #define MMA(ai, bj, At_, Bt_) do { __builtin_amdgcn_s_setprio(1); \
;     for (int m = 0; m < 4; ++m) for (int n = 0; n < 2; ++n) for (int k = 0; k < 2; ++k) \
;       acc[ai][bj][m][n] = __builtin_amdgcn_mfma_f32_16x16x32_bf16(At_[m][k], Bt_[n][k], acc[ai][bj][m][n], 0, 0, 0); \
;     __builtin_amdgcn_s_setprio(0); } while (0)
; #define WAIT_L(n) asm volatile("s_waitcnt lgkmcnt(" #n ")" ::: "memory")
; #define BAR __builtin_amdgcn_s_barrier()
; #define SCHED __builtin_amdgcn_sched_barrier(0)
; template <int EPI>
; __device__ __forceinline__ void gemm_phase(const GemmDesc d, u16* shm, unsigned sx, unsigned srank, unsigned snloc) {
;     ...
;         WAIT_L(8); BAR; MMA(0, 0, At, B0); BAR; SCHED;
;         LDB(B1, 1, 1); STAGE_B(B3, B3h, vh, 1, 0);
;         BAR; MMA(0, 1, At, B1); BAR;
;         LDA(At, 1, 1); STAGE_A(A3, 1, 0);
	s_setprio 1
	s_waitcnt lgkmcnt(7)
	v_mfma_f32_16x16x32_bf16 v[124:127], v[156:159], v[140:143], v[124:127]
	v_mfma_f32_16x16x32_bf16 v[116:119], v[156:159], v[148:151], v[116:119]
	s_waitcnt lgkmcnt(5)
	v_mfma_f32_16x16x32_bf16 v[108:111], v[164:167], v[140:143], v[108:111]
	v_mfma_f32_16x16x32_bf16 v[100:103], v[164:167], v[148:151], v[100:103]
	s_waitcnt lgkmcnt(3)
	v_mfma_f32_16x16x32_bf16 v[92:95], v[172:175], v[140:143], v[92:95]
	v_mfma_f32_16x16x32_bf16 v[84:87], v[172:175], v[148:151], v[84:87]
	s_waitcnt lgkmcnt(1)
	v_mfma_f32_16x16x32_bf16 v[76:79], v[190:193], v[140:143], v[76:79]
	v_mfma_f32_16x16x32_bf16 v[68:71], v[190:193], v[148:151], v[68:71]
	v_mfma_f32_16x16x32_bf16 v[124:127], v[160:163], v[144:147], v[124:127]
	v_mfma_f32_16x16x32_bf16 v[116:119], v[160:163], v[152:155], v[116:119]
	v_mfma_f32_16x16x32_bf16 v[108:111], v[168:171], v[144:147], v[108:111]
	v_mfma_f32_16x16x32_bf16 v[100:103], v[168:171], v[152:155], v[100:103]
	v_mfma_f32_16x16x32_bf16 v[92:95], v[178:181], v[144:147], v[92:95]
	v_mfma_f32_16x16x32_bf16 v[84:87], v[178:181], v[152:155], v[84:87]
	s_waitcnt lgkmcnt(0)
	v_mfma_f32_16x16x32_bf16 v[76:79], v[194:197], v[144:147], v[76:79]
	v_mfma_f32_16x16x32_bf16 v[68:71], v[194:197], v[152:155], v[68:71]
	s_setprio 0
	s_barrier
	ds_read_b128 v[198:201], v138
	ds_read_b128 v[202:205], v138 offset:1024
	ds_read_b128 v[206:209], v138 offset:2048
	ds_read_b128 v[210:213], v138 offset:3072
	s_mov_b32 m0, s71
	s_nop 0
	global_load_lds_dwordx4 v130, s[40:41]
	s_mov_b32 m0, s72
	s_nop 0
	global_load_lds_dwordx4 v130, s[42:43]
	s_barrier
	s_setprio 1
	s_waitcnt lgkmcnt(3)
	v_mfma_f32_16x16x32_bf16 v[120:123], v[156:159], v[198:201], v[120:123]
	s_waitcnt lgkmcnt(1)
	v_mfma_f32_16x16x32_bf16 v[112:115], v[156:159], v[206:209], v[112:115]
	v_mfma_f32_16x16x32_bf16 v[104:107], v[164:167], v[198:201], v[104:107]
	v_mfma_f32_16x16x32_bf16 v[96:99], v[164:167], v[206:209], v[96:99]
	v_mfma_f32_16x16x32_bf16 v[88:91], v[172:175], v[198:201], v[88:91]
	v_mfma_f32_16x16x32_bf16 v[80:83], v[172:175], v[206:209], v[80:83]
	v_mfma_f32_16x16x32_bf16 v[72:75], v[190:193], v[198:201], v[72:75]
	v_mfma_f32_16x16x32_bf16 v[64:67], v[190:193], v[206:209], v[64:67]
	v_mfma_f32_16x16x32_bf16 v[120:123], v[160:163], v[202:205], v[120:123]
	s_waitcnt lgkmcnt(0)
	v_mfma_f32_16x16x32_bf16 v[112:115], v[160:163], v[210:213], v[112:115]
	v_mfma_f32_16x16x32_bf16 v[104:107], v[168:171], v[202:205], v[104:107]
	v_mfma_f32_16x16x32_bf16 v[96:99], v[168:171], v[210:213], v[96:99]
	v_mfma_f32_16x16x32_bf16 v[88:91], v[178:181], v[202:205], v[88:91]
	v_mfma_f32_16x16x32_bf16 v[80:83], v[178:181], v[210:213], v[80:83]
	v_mfma_f32_16x16x32_bf16 v[72:75], v[194:197], v[202:205], v[72:75]
	v_mfma_f32_16x16x32_bf16 v[64:67], v[194:197], v[210:213], v[64:67]
	s_setprio 0
	s_barrier
	ds_read_b128 v[156:159], v132 offset:49152
	ds_read_b128 v[160:163], v132 offset:50176
	ds_read_b128 v[164:167], v133 offset:49152
	ds_read_b128 v[168:171], v133 offset:50176
	ds_read_b128 v[172:175], v134 offset:49152
	ds_read_b128 v[178:181], v134 offset:50176
	ds_read_b128 v[190:193], v135 offset:49152
	ds_read_b128 v[194:197], v135 offset:50176
	s_mov_b32 m0, s73
	s_nop 0
	global_load_lds_dwordx4 v130, s[22:23]
	s_mov_b32 m0, s76
	s_nop 0
	global_load_lds_dwordx4 v130, s[30:31]
	s_barrier
; #define STAGE_A(Ak_, b, h) do { const char* _s = (Ak_) + (h) * sHA; \
;     glds16(lds0 + ((b) * 2 + (h)) * (HT * 2), voffA, _s); glds16(lds0 + ((b) * 2 + (h)) * (HT * 2) + 8192, voffA, _s + s2A); } while (0)
; #define STAGE_B(Bk_, Bkh_, vh_, b, h) do { const char* _s = (h) ? (Bkh_) : (Bk_); const unsigned _v0 = (h) ? (vh_)[0] : voffB, _v1 = (h) ? (vh_)[1] : voffB; const long _d = (h) ? s2Bh : s2B; \
;     glds16(lds0 + (4 + (b) * 2 + (h)) * (HT * 2), _v0, _s); glds16(lds0 + (4 + (b) * 2 + (h)) * (HT * 2) + 8192, _v1, _s + _d); } while (0)
; #define LDA(dst, b, h) for (int m = 0; m < 4; ++m) for (int k = 0; k < 2; ++k) \
;     dst[m][k] = *reinterpret_cast<const bf16x8*>((char*)SA(b, h) + lds_byte(wr * 64 + m * 16 + fr, k * 32 + fq * 8))
; #define MMA(ai, bj, At_, Bt_) do { __builtin_amdgcn_s_setprio(1); \
;     for (int m = 0; m < 4; ++m) for (int n = 0; n < 2; ++n) for (int k = 0; k < 2; ++k) \
;       acc[ai][bj][m][n] = __builtin_amdgcn_mfma_f32_16x16x32_bf16(At_[m][k], Bt_[n][k], acc[ai][bj][m][n], 0, 0, 0); \
;     __builtin_amdgcn_s_setprio(0); } while (0)
; #define WAIT_V(n) asm volatile("s_waitcnt vmcnt(" #n ")" ::: "memory")
; #define BAR __builtin_amdgcn_s_barrier()
; #define SCHED __builtin_amdgcn_sched_barrier(0)
; template <int EPI>
; __device__ __forceinline__ void gemm_phase(const GemmDesc d, u16* shm, unsigned sx, unsigned srank, unsigned snloc) {
;     ...
;         LDA(At, 1, 1); STAGE_A(A3, 1, 0);
;         BAR; MMA(1, 0, At, B0); BAR; SCHED;
;         STAGE_B(B3, B3h, vh, 1, 1);
;         WAIT_V(6); BAR; MMA(1, 1, At, B1); BAR;
;       }
	s_setprio 1
	s_waitcnt lgkmcnt(7)
	v_mfma_f32_16x16x32_bf16 v[60:63], v[156:159], v[140:143], v[60:63]
	v_mfma_f32_16x16x32_bf16 v[52:55], v[156:159], v[148:151], v[52:55]
	s_waitcnt lgkmcnt(5)
	v_mfma_f32_16x16x32_bf16 v[44:47], v[164:167], v[140:143], v[44:47]
	v_mfma_f32_16x16x32_bf16 v[36:39], v[164:167], v[148:151], v[36:39]
	s_waitcnt lgkmcnt(3)
	v_mfma_f32_16x16x32_bf16 v[28:31], v[172:175], v[140:143], v[28:31]
	v_mfma_f32_16x16x32_bf16 v[20:23], v[172:175], v[148:151], v[20:23]
	s_waitcnt lgkmcnt(1)
	v_mfma_f32_16x16x32_bf16 v[12:15], v[190:193], v[140:143], v[12:15]
	v_mfma_f32_16x16x32_bf16 v[4:7], v[190:193], v[148:151], v[4:7]
	v_mfma_f32_16x16x32_bf16 v[60:63], v[160:163], v[144:147], v[60:63]
	v_mfma_f32_16x16x32_bf16 v[52:55], v[160:163], v[152:155], v[52:55]
	v_mfma_f32_16x16x32_bf16 v[44:47], v[168:171], v[144:147], v[44:47]
	v_mfma_f32_16x16x32_bf16 v[36:39], v[168:171], v[152:155], v[36:39]
	v_mfma_f32_16x16x32_bf16 v[28:31], v[178:181], v[144:147], v[28:31]
	v_mfma_f32_16x16x32_bf16 v[20:23], v[178:181], v[152:155], v[20:23]
	s_waitcnt lgkmcnt(0)
	v_mfma_f32_16x16x32_bf16 v[12:15], v[194:197], v[144:147], v[12:15]
	v_mfma_f32_16x16x32_bf16 v[4:7], v[194:197], v[152:155], v[4:7]
	s_setprio 0
	s_barrier
	s_mov_b32 m0, s77
	s_nop 0
	global_load_lds_dwordx4 v130, s[18:19]
	s_mov_b32 m0, s78
	s_nop 0
	global_load_lds_dwordx4 v130, s[4:5]
	s_mov_b64 s[34:35], s[38:39]
	s_mov_b32 s20, s21
	s_add_i32 s21, s20, 2
	s_add_u32 s0, s34, 0xfffc0080
	s_addc_u32 s1, s35, -1
	s_cmp_lt_u32 s20, 14
	s_cselect_b32 s94, s90, s16
	s_cselect_b32 s51, s1, s15
	s_cselect_b32 s50, s0, s14
	s_cselect_b32 s95, s91, s17
	s_cselect_b32 s47, s93, s25
	s_cselect_b32 s46, s92, s24
	s_add_u32 s40, s94, 0x80
	s_addc_u32 s41, s95, 0
	s_add_u32 s22, s50, 0x80
	s_addc_u32 s23, s51, 0
	s_add_u32 s96, s34, 0x20000
	s_addc_u32 s97, s35, 0
	s_add_u32 s0, s94, 0x20000
	s_addc_u32 s1, s95, 0
	s_add_u32 s52, s50, 0x20000
	s_addc_u32 s53, s51, 0
	s_add_u32 s48, s46, 0x20000
	s_addc_u32 s49, s47, 0
	s_add_u32 s44, s50, 0x40000
	s_addc_u32 s45, s51, 0
	s_add_u32 s28, s50, 0x60000
	s_addc_u32 s29, s51, 0
	s_add_u32 s42, s94, 0x20080
	s_addc_u32 s43, s95, 0
	s_add_u32 s30, s50, 0x20080
	s_addc_u32 s31, s51, 0
	s_add_u32 s18, s46, 0x80
	s_addc_u32 s19, s47, 0
	s_add_u32 s4, s46, 0x20080
	s_addc_u32 s5, s47, 0
	s_add_u32 s38, s34, 0x100
	s_addc_u32 s39, s35, 0
	s_add_u32 s90, s90, 0x100
	s_addc_u32 s91, s91, 0
	s_add_u32 s92, s92, 0x100
	s_addc_u32 s93, s93, 0
	s_waitcnt vmcnt(6)
	s_barrier
	s_setprio 1
	v_mfma_f32_16x16x32_bf16 v[56:59], v[156:159], v[198:201], v[56:59]
	v_mfma_f32_16x16x32_bf16 v[48:51], v[156:159], v[206:209], v[48:51]
	v_mfma_f32_16x16x32_bf16 v[40:43], v[164:167], v[198:201], v[40:43]
	v_mfma_f32_16x16x32_bf16 v[32:35], v[164:167], v[206:209], v[32:35]
	v_mfma_f32_16x16x32_bf16 v[24:27], v[172:175], v[198:201], v[24:27]
	v_mfma_f32_16x16x32_bf16 v[16:19], v[172:175], v[206:209], v[16:19]
	v_mfma_f32_16x16x32_bf16 v[8:11], v[190:193], v[198:201], v[8:11]
	v_mfma_f32_16x16x32_bf16 v[0:3], v[190:193], v[206:209], v[0:3]
	v_mfma_f32_16x16x32_bf16 v[56:59], v[160:163], v[202:205], v[56:59]
	v_mfma_f32_16x16x32_bf16 v[48:51], v[160:163], v[210:213], v[48:51]
	v_mfma_f32_16x16x32_bf16 v[40:43], v[168:171], v[202:205], v[40:43]
	v_mfma_f32_16x16x32_bf16 v[32:35], v[168:171], v[210:213], v[32:35]
	v_mfma_f32_16x16x32_bf16 v[24:27], v[178:181], v[202:205], v[24:27]
	v_mfma_f32_16x16x32_bf16 v[16:19], v[178:181], v[210:213], v[16:19]
	v_mfma_f32_16x16x32_bf16 v[8:11], v[194:197], v[202:205], v[8:11]
	v_mfma_f32_16x16x32_bf16 v[0:3], v[194:197], v[210:213], v[0:3]
	s_setprio 0
	s_cmp_lt_u32 s20, 16
	s_barrier
	s_cbranch_scc1 .Lgu_kloop
	s_and_saveexec_b64 s[4:5], s[8:9]
	s_cbranch_execz .LBB0_1450
	s_barrier

; __device__ __forceinline__ unsigned pack2(float lo, float hi) { unsigned r; asm volatile("v_cvt_pk_bf16_f32 %0, %1, %2" : "=v"(r) : "v"(lo), "v"(hi)); return r; }
; template <int EPI>
; __device__ __forceinline__ void gemm_phase(const GemmDesc d, u16* shm, unsigned sx, unsigned srank, unsigned snloc) {
;     ...
;       if constexpr (EPI == E_SWIGLU) {
;         using f32x2 = __attribute__((ext_vector_type(2))) float;
;         const int sw_row = lane2 >> 2, sw_c8 = (lane2 & 3) * 8;
;         u16* sw_base = d.outb + ((size_t)(brow >> 7) * 44 + pn * 2 + (wc2 >> 1)) * 8192
;                      + ((((sw_row * 64 + sw_c8 * 2) ^ ((sw_row >> 3) << 5)) + (wr2 * 8 + (wc2 & 1)) * 1024) >> 1);
; #pragma unroll
;         for (int ai = 0; ai < 2; ++ai)
; #pragma unroll
;           for (int m = 0; m < 4; ++m) {
;             const f32x4 r4 = *(const f32x4*)&lr[ai * 128 + wr2 * 64 + m * 16 + fq2 * 4];
;             const f32x4 rc4 = r4 * (-1.4426950408889634f), rr4 = r4 * r4;
; #pragma unroll
;             for (int n = 0; n < 2; ++n)
; #pragma unroll
;               for (int jp = 0; jp < 4; jp += 2) {
;                 const f32x2 a = {acc[ai][0][m][n][jp], acc[ai][0][m][n][jp + 1]}, b = {acc[ai][1][m][n][jp], acc[ai][1][m][n][jp + 1]};
;                 const f32x2 rc = {rc4[jp], rc4[jp + 1]}, rr = {rr4[jp], rr4[jp + 1]};
;                 const f32x2 tl = a * rc;
;                 f32x2 dd = {__builtin_amdgcn_exp2f(tl[0]), __builtin_amdgcn_exp2f(tl[1])};
;                 dd = dd + 1.0f;
;                 const f32x2 s = {__builtin_amdgcn_rcpf(dd[0]), __builtin_amdgcn_rcpf(dd[1])};
;                 const f32x2 o = (a * b) * (rr * s);
;                 stg[(fq2 * 4 + jp) * 36 + n * 16 + fr2] = o[0];
;                 stg[(fq2 * 4 + jp + 1) * 36 + n * 16 + fr2] = o[1];
;               }
;             {
;               const f32x4 v0 = *(const f32x4*)&stg[sw_row * 36 + sw_c8], v1 = *(const f32x4*)&stg[sw_row * 36 + sw_c8 + 4];
;               u32x4 w = {pack2(v0[0], v0[1]), pack2(v0[2], v0[3]), pack2(v1[0], v1[1]), pack2(v1[2], v1[3])};
;               __builtin_nontemporal_store(w, (u32x4*)(sw_base + (size_t)ai * (44 * 8192) + m * 1024));
;             }
.LBB0_1452:
	s_or_b64 exec, exec, s[4:5]
	v_ashrrev_i32_e32 v141, 6, v139
	s_movk_i32 s0, 0x900
	v_mul_lo_u32 v128, v141, s0
	s_lshl_b32 s0, s70, 8
	s_and_b32 s18, s0, 0x100
	v_add_u32_e32 v156, s83, v128
	s_lshl_b32 s0, s18, 2
	v_lshlrev_b32_e32 v128, 3, v139
	s_add_i32 s0, s0, 0
	v_bfe_u32 v145, v139, 2, 4
	v_and_b32_e32 v146, 24, v128
	s_lshl_b32 s5, s88, 1
	s_add_i32 s0, s0, 0x20000
	s_lshl_b32 s1, s89, 1
	s_mul_i32 s4, s89, 0x58
	s_ashr_i32 s19, s5, 31
	v_lshlrev_b32_e32 v142, 6, v145
	v_lshlrev_b32_e32 v143, 1, v146
	v_and_b32_e32 v147, 32, v139
	s_mul_hi_i32 s1, s1, 44
	s_add_u32 s4, s4, s5
	v_lshrrev_b32_e32 v128, 1, v141
	v_bitop3_b32 v142, v142, v147, v143 bitop3:0x36
	v_lshlrev_b32_e32 v143, 5, v139
	v_lshlrev_b32_e32 v141, 10, v141
	s_addc_u32 s1, s1, s19
	v_and_b32_e32 v143, 0xffffe000, v143
	v_and_b32_e32 v141, 0x400, v141
	v_and_or_b32 v128, v128, 1, s4
	v_mov_b32_e32 v129, s1
	v_or3_b32 v141, v141, v143, v142
	v_lshlrev_b64 v[128:129], 14, v[128:129]
	v_ashrrev_i32_e32 v142, 1, v141
	v_lshrrev_b32_e32 v144, 2, v139
	v_lshl_add_u64 v[128:129], s[12:13], 0, v[128:129]
	v_ashrrev_i32_e32 v143, 31, v142
	v_lshl_add_u64 v[128:129], v[142:143], 1, v[128:129]
	v_and_b32_e32 v143, 12, v144
	v_and_b32_e32 v141, 0xffffff00, v139
	v_lshlrev_b32_e32 v142, 2, v143
	v_add3_u32 v142, s0, v141, v142
	v_lshlrev_b32_e32 v141, 2, v139
	v_and_b32_e32 v157, 60, v141
	v_mul_u32_u24_e32 v141, 0x90, v145
	v_lshlrev_b32_e32 v144, 2, v146
	v_add3_u32 v141, v156, v141, v144
	v_mul_u32_u24_e32 v144, 36, v143
	v_lshlrev_b32_e32 v144, 2, v144
	v_add3_u32 v143, v156, v157, v144
	ds_read_b128 v[150:153], v142
	ds_read_b128 v[154:157], v142 offset:64
	s_mov_b32 s0, 0x1000
	s_mov_b32 s1, 0
	v_lshl_add_u64 v[144:145], v[128:129], 0, s[0:1]
	s_mov_b32 s0, 0xb0000
	v_pk_mul_f32 v[120:121], v[124:125], v[120:121]
	v_pk_mul_f32 v[122:123], v[126:127], v[122:123]
	v_lshl_add_u64 v[146:147], v[128:129], 0, s[0:1]
	s_mov_b32 s0, 0xb1000
	v_pk_mul_f32 v[112:113], v[116:117], v[112:113]
	v_pk_mul_f32 v[114:115], v[118:119], v[114:115]
	v_lshl_add_u64 v[148:149], v[128:129], 0, s[0:1]
	s_waitcnt lgkmcnt(1)
	v_pk_mul_f32 v[158:159], v[150:151], v[150:151]
	v_pk_mul_f32 v[160:161], v[152:153], v[152:153]
	v_pk_mul_f32 v[150:151], v[150:151], s[86:87] op_sel_hi:[1,0]
	v_pk_mul_f32 v[152:153], v[152:153], s[86:87] op_sel_hi:[1,0]
	v_pk_mul_f32 v[124:125], v[124:125], v[150:151]
	v_pk_mul_f32 v[126:127], v[126:127], v[152:153]
	v_pk_mul_f32 v[116:117], v[116:117], v[150:151]
	v_pk_mul_f32 v[118:119], v[118:119], v[152:153]
	v_exp_f32_e32 v124, v124
	v_exp_f32_e32 v125, v125
	v_exp_f32_e32 v126, v126
	v_exp_f32_e32 v127, v127
	v_exp_f32_e32 v116, v116
	v_exp_f32_e32 v117, v117
	v_exp_f32_e32 v118, v118
	v_exp_f32_e32 v119, v119
	v_pk_mul_f32 v[104:105], v[108:109], v[104:105]
	v_pk_mul_f32 v[106:107], v[110:111], v[106:107]
	v_pk_mul_f32 v[96:97], v[100:101], v[96:97]
	v_pk_mul_f32 v[98:99], v[102:103], v[98:99]
	v_pk_add_f32 v[124:125], v[124:125], 1.0 op_sel_hi:[1,0]
	v_pk_add_f32 v[126:127], v[126:127], 1.0 op_sel_hi:[1,0]
	v_pk_add_f32 v[116:117], v[116:117], 1.0 op_sel_hi:[1,0]
	v_pk_add_f32 v[118:119], v[118:119], 1.0 op_sel_hi:[1,0]
	v_rcp_f32_e32 v124, v124
	v_rcp_f32_e32 v125, v125
	v_rcp_f32_e32 v126, v126
	v_rcp_f32_e32 v127, v127
	v_rcp_f32_e32 v116, v116
	v_rcp_f32_e32 v117, v117
	v_rcp_f32_e32 v118, v118
	v_rcp_f32_e32 v119, v119
	v_pk_mul_f32 v[124:125], v[158:159], v[124:125]
	v_pk_mul_f32 v[126:127], v[160:161], v[126:127]
	v_pk_mul_f32 v[116:117], v[158:159], v[116:117]
	v_pk_mul_f32 v[118:119], v[160:161], v[118:119]
	v_pk_mul_f32 v[120:121], v[120:121], v[124:125]
	v_pk_mul_f32 v[122:123], v[122:123], v[126:127]
	v_pk_mul_f32 v[112:113], v[112:113], v[116:117]
	v_pk_mul_f32 v[114:115], v[114:115], v[118:119]
	ds_write2_b32 v143, v120, v112 offset1:16
	ds_write2_b32 v143, v121, v113 offset0:36 offset1:52
	ds_write2_b32 v143, v122, v114 offset0:72 offset1:88
	ds_write2_b32 v143, v123, v115 offset0:108 offset1:124
	ds_read_b128 v[166:169], v141
	ds_read_b128 v[170:173], v141 offset:16
	ds_read_b128 v[150:153], v142 offset:128
	s_waitcnt lgkmcnt(7)
	v_pk_mul_f32 v[162:163], v[154:155], v[154:155]
	v_pk_mul_f32 v[164:165], v[156:157], v[156:157]
	v_pk_mul_f32 v[154:155], v[154:155], s[86:87] op_sel_hi:[1,0]
	v_pk_mul_f32 v[156:157], v[156:157], s[86:87] op_sel_hi:[1,0]
	v_pk_mul_f32 v[108:109], v[108:109], v[154:155]
	v_pk_mul_f32 v[110:111], v[110:111], v[156:157]
	v_pk_mul_f32 v[100:101], v[100:101], v[154:155]
	v_pk_mul_f32 v[102:103], v[102:103], v[156:157]
	v_exp_f32_e32 v108, v108
	v_exp_f32_e32 v109, v109
	v_exp_f32_e32 v110, v110
	v_exp_f32_e32 v111, v111
	v_exp_f32_e32 v100, v100
	v_exp_f32_e32 v101, v101
	v_exp_f32_e32 v102, v102
	v_exp_f32_e32 v103, v103
	v_pk_mul_f32 v[88:89], v[92:93], v[88:89]
	v_pk_mul_f32 v[90:91], v[94:95], v[90:91]
	v_pk_mul_f32 v[80:81], v[84:85], v[80:81]
	v_pk_mul_f32 v[82:83], v[86:87], v[82:83]
	s_waitcnt lgkmcnt(1)
	v_cvt_pk_bf16_f32 v166, v166, v167
	v_cvt_pk_bf16_f32 v167, v168, v169
	v_cvt_pk_bf16_f32 v168, v170, v171
	v_cvt_pk_bf16_f32 v169, v172, v173
	global_store_dwordx4 v[128:129], v[166:169], off nt
	v_pk_add_f32 v[108:109], v[108:109], 1.0 op_sel_hi:[1,0]
	v_pk_add_f32 v[110:111], v[110:111], 1.0 op_sel_hi:[1,0]
	v_pk_add_f32 v[100:101], v[100:101], 1.0 op_sel_hi:[1,0]
	v_pk_add_f32 v[102:103], v[102:103], 1.0 op_sel_hi:[1,0]
	v_rcp_f32_e32 v108, v108
	v_rcp_f32_e32 v109, v109
	v_rcp_f32_e32 v110, v110
	v_rcp_f32_e32 v111, v111
	v_rcp_f32_e32 v100, v100
	v_rcp_f32_e32 v101, v101
	v_rcp_f32_e32 v102, v102
	v_rcp_f32_e32 v103, v103
	v_pk_mul_f32 v[108:109], v[162:163], v[108:109]
	v_pk_mul_f32 v[110:111], v[164:165], v[110:111]
	v_pk_mul_f32 v[100:101], v[162:163], v[100:101]
	v_pk_mul_f32 v[102:103], v[164:165], v[102:103]
	v_pk_mul_f32 v[104:105], v[104:105], v[108:109]
	v_pk_mul_f32 v[106:107], v[106:107], v[110:111]
	v_pk_mul_f32 v[96:97], v[96:97], v[100:101]
	v_pk_mul_f32 v[98:99], v[98:99], v[102:103]
	ds_write2_b32 v143, v104, v96 offset1:16
	ds_write2_b32 v143, v105, v97 offset0:36 offset1:52
	ds_write2_b32 v143, v106, v98 offset0:72 offset1:88
	ds_write2_b32 v143, v107, v99 offset0:108 offset1:124
	ds_read_b128 v[190:193], v141
	ds_read_b128 v[194:197], v141 offset:16
	ds_read_b128 v[154:157], v142 offset:192
	s_waitcnt lgkmcnt(7)
; __device__ __forceinline__ unsigned pack2(float lo, float hi) { unsigned r; asm volatile("v_cvt_pk_bf16_f32 %0, %1, %2" : "=v"(r) : "v"(lo), "v"(hi)); return r; }
; template <int EPI>
; __device__ __forceinline__ void gemm_phase(const GemmDesc d, u16* shm, unsigned sx, unsigned srank, unsigned snloc) {
;     ...
;           for (int m = 0; m < 4; ++m) {
;             const f32x4 r4 = *(const f32x4*)&lr[ai * 128 + wr2 * 64 + m * 16 + fq2 * 4];
;             const f32x4 rc4 = r4 * (-1.4426950408889634f), rr4 = r4 * r4;
; #pragma unroll
;             for (int n = 0; n < 2; ++n)
; #pragma unroll
;               for (int jp = 0; jp < 4; jp += 2) {
;                 const f32x2 a = {acc[ai][0][m][n][jp], acc[ai][0][m][n][jp + 1]}, b = {acc[ai][1][m][n][jp], acc[ai][1][m][n][jp + 1]};
;                 const f32x2 rc = {rc4[jp], rc4[jp + 1]}, rr = {rr4[jp], rr4[jp + 1]};
;                 const f32x2 tl = a * rc;
;                 f32x2 dd = {__builtin_amdgcn_exp2f(tl[0]), __builtin_amdgcn_exp2f(tl[1])};
;                 dd = dd + 1.0f;
;                 const f32x2 s = {__builtin_amdgcn_rcpf(dd[0]), __builtin_amdgcn_rcpf(dd[1])};
;                 const f32x2 o = (a * b) * (rr * s);
;                 stg[(fq2 * 4 + jp) * 36 + n * 16 + fr2] = o[0];
;                 stg[(fq2 * 4 + jp + 1) * 36 + n * 16 + fr2] = o[1];
;               }
;             {
;               const f32x4 v0 = *(const f32x4*)&stg[sw_row * 36 + sw_c8], v1 = *(const f32x4*)&stg[sw_row * 36 + sw_c8 + 4];
;               u32x4 w = {pack2(v0[0], v0[1]), pack2(v0[2], v0[3]), pack2(v1[0], v1[1]), pack2(v1[2], v1[3])};
;               __builtin_nontemporal_store(w, (u32x4*)(sw_base + (size_t)ai * (44 * 8192) + m * 1024));
;             }
	v_pk_mul_f32 v[158:159], v[150:151], v[150:151]
	v_pk_mul_f32 v[160:161], v[152:153], v[152:153]
	v_pk_mul_f32 v[150:151], v[150:151], s[86:87] op_sel_hi:[1,0]
	v_pk_mul_f32 v[152:153], v[152:153], s[86:87] op_sel_hi:[1,0]
	v_pk_mul_f32 v[92:93], v[92:93], v[150:151]
	v_pk_mul_f32 v[94:95], v[94:95], v[152:153]
	v_pk_mul_f32 v[84:85], v[84:85], v[150:151]
	v_pk_mul_f32 v[86:87], v[86:87], v[152:153]
	v_exp_f32_e32 v92, v92
	v_exp_f32_e32 v93, v93
	v_exp_f32_e32 v94, v94
	v_exp_f32_e32 v95, v95
	v_exp_f32_e32 v84, v84
	v_exp_f32_e32 v85, v85
	v_exp_f32_e32 v86, v86
	v_exp_f32_e32 v87, v87
	v_pk_mul_f32 v[72:73], v[76:77], v[72:73]
	v_pk_mul_f32 v[74:75], v[78:79], v[74:75]
	v_pk_mul_f32 v[64:65], v[68:69], v[64:65]
	v_pk_mul_f32 v[66:67], v[70:71], v[66:67]
	s_waitcnt lgkmcnt(1)
	v_cvt_pk_bf16_f32 v190, v190, v191
	v_cvt_pk_bf16_f32 v191, v192, v193
	v_cvt_pk_bf16_f32 v192, v194, v195
	v_cvt_pk_bf16_f32 v193, v196, v197
	global_store_dwordx4 v[128:129], v[190:193], off offset:2048 nt
	v_pk_add_f32 v[92:93], v[92:93], 1.0 op_sel_hi:[1,0]
	v_pk_add_f32 v[94:95], v[94:95], 1.0 op_sel_hi:[1,0]
	v_pk_add_f32 v[84:85], v[84:85], 1.0 op_sel_hi:[1,0]
	v_pk_add_f32 v[86:87], v[86:87], 1.0 op_sel_hi:[1,0]
	v_rcp_f32_e32 v92, v92
	v_rcp_f32_e32 v93, v93
	v_rcp_f32_e32 v94, v94
	v_rcp_f32_e32 v95, v95
	v_rcp_f32_e32 v84, v84
	v_rcp_f32_e32 v85, v85
	v_rcp_f32_e32 v86, v86
	v_rcp_f32_e32 v87, v87
	v_pk_mul_f32 v[92:93], v[158:159], v[92:93]
	v_pk_mul_f32 v[94:95], v[160:161], v[94:95]
	v_pk_mul_f32 v[84:85], v[158:159], v[84:85]
	v_pk_mul_f32 v[86:87], v[160:161], v[86:87]
	v_pk_mul_f32 v[88:89], v[88:89], v[92:93]
	v_pk_mul_f32 v[90:91], v[90:91], v[94:95]
	v_pk_mul_f32 v[80:81], v[80:81], v[84:85]
	v_pk_mul_f32 v[82:83], v[82:83], v[86:87]
	ds_write2_b32 v143, v88, v80 offset1:16
	ds_write2_b32 v143, v89, v81 offset0:36 offset1:52
	ds_write2_b32 v143, v90, v82 offset0:72 offset1:88
	ds_write2_b32 v143, v91, v83 offset0:108 offset1:124
	ds_read_b128 v[166:169], v141
	ds_read_b128 v[170:173], v141 offset:16
	ds_read_b128 v[150:153], v142 offset:512
	s_waitcnt lgkmcnt(7)
	v_pk_mul_f32 v[162:163], v[154:155], v[154:155]
	v_pk_mul_f32 v[164:165], v[156:157], v[156:157]
	v_pk_mul_f32 v[154:155], v[154:155], s[86:87] op_sel_hi:[1,0]
	v_pk_mul_f32 v[156:157], v[156:157], s[86:87] op_sel_hi:[1,0]
	v_pk_mul_f32 v[76:77], v[76:77], v[154:155]
	v_pk_mul_f32 v[78:79], v[78:79], v[156:157]
	v_pk_mul_f32 v[68:69], v[68:69], v[154:155]
	v_pk_mul_f32 v[70:71], v[70:71], v[156:157]
	v_exp_f32_e32 v76, v76
	v_exp_f32_e32 v77, v77
	v_exp_f32_e32 v78, v78
	v_exp_f32_e32 v79, v79
	v_exp_f32_e32 v68, v68
	v_exp_f32_e32 v69, v69
	v_exp_f32_e32 v70, v70
	v_exp_f32_e32 v71, v71
	v_pk_mul_f32 v[56:57], v[60:61], v[56:57]
	v_pk_mul_f32 v[58:59], v[62:63], v[58:59]
	v_pk_mul_f32 v[48:49], v[52:53], v[48:49]
	v_pk_mul_f32 v[50:51], v[54:55], v[50:51]
	s_waitcnt lgkmcnt(1)
	v_cvt_pk_bf16_f32 v166, v166, v167
	v_cvt_pk_bf16_f32 v167, v168, v169
	v_cvt_pk_bf16_f32 v168, v170, v171
	v_cvt_pk_bf16_f32 v169, v172, v173
	global_store_dwordx4 v[144:145], v[166:169], off nt
	v_pk_add_f32 v[76:77], v[76:77], 1.0 op_sel_hi:[1,0]
	v_pk_add_f32 v[78:79], v[78:79], 1.0 op_sel_hi:[1,0]
	v_pk_add_f32 v[68:69], v[68:69], 1.0 op_sel_hi:[1,0]
	v_pk_add_f32 v[70:71], v[70:71], 1.0 op_sel_hi:[1,0]
	v_rcp_f32_e32 v76, v76
	v_rcp_f32_e32 v77, v77
	v_rcp_f32_e32 v78, v78
	v_rcp_f32_e32 v79, v79
	v_rcp_f32_e32 v68, v68
	v_rcp_f32_e32 v69, v69
	v_rcp_f32_e32 v70, v70
	v_rcp_f32_e32 v71, v71
	v_pk_mul_f32 v[76:77], v[162:163], v[76:77]
	v_pk_mul_f32 v[78:79], v[164:165], v[78:79]
	v_pk_mul_f32 v[68:69], v[162:163], v[68:69]
	v_pk_mul_f32 v[70:71], v[164:165], v[70:71]
	v_pk_mul_f32 v[72:73], v[72:73], v[76:77]
	v_pk_mul_f32 v[74:75], v[74:75], v[78:79]
	v_pk_mul_f32 v[64:65], v[64:65], v[68:69]
	v_pk_mul_f32 v[66:67], v[66:67], v[70:71]
	ds_write2_b32 v143, v72, v64 offset1:16
	ds_write2_b32 v143, v73, v65 offset0:36 offset1:52
	ds_write2_b32 v143, v74, v66 offset0:72 offset1:88
	ds_write2_b32 v143, v75, v67 offset0:108 offset1:124
	ds_read_b128 v[190:193], v141
	ds_read_b128 v[194:197], v141 offset:16
	ds_read_b128 v[154:157], v142 offset:576
	s_waitcnt lgkmcnt(7)
	v_pk_mul_f32 v[158:159], v[150:151], v[150:151]
	v_pk_mul_f32 v[160:161], v[152:153], v[152:153]
	v_pk_mul_f32 v[150:151], v[150:151], s[86:87] op_sel_hi:[1,0]
	v_pk_mul_f32 v[152:153], v[152:153], s[86:87] op_sel_hi:[1,0]
	v_pk_mul_f32 v[60:61], v[60:61], v[150:151]
	v_pk_mul_f32 v[62:63], v[62:63], v[152:153]
	v_pk_mul_f32 v[52:53], v[52:53], v[150:151]
	v_pk_mul_f32 v[54:55], v[54:55], v[152:153]
	v_exp_f32_e32 v60, v60
	v_exp_f32_e32 v61, v61
	v_exp_f32_e32 v62, v62
	v_exp_f32_e32 v63, v63
	v_exp_f32_e32 v52, v52
	v_exp_f32_e32 v53, v53
	v_exp_f32_e32 v54, v54
	v_exp_f32_e32 v55, v55
	v_pk_mul_f32 v[40:41], v[44:45], v[40:41]
	v_pk_mul_f32 v[42:43], v[46:47], v[42:43]
	v_pk_mul_f32 v[32:33], v[36:37], v[32:33]
	v_pk_mul_f32 v[34:35], v[38:39], v[34:35]
	s_waitcnt lgkmcnt(1)
	v_cvt_pk_bf16_f32 v190, v190, v191
	v_cvt_pk_bf16_f32 v191, v192, v193
	v_cvt_pk_bf16_f32 v192, v194, v195
	v_cvt_pk_bf16_f32 v193, v196, v197
	global_store_dwordx4 v[144:145], v[190:193], off offset:2048 nt
	v_pk_add_f32 v[60:61], v[60:61], 1.0 op_sel_hi:[1,0]
	v_pk_add_f32 v[62:63], v[62:63], 1.0 op_sel_hi:[1,0]
	v_pk_add_f32 v[52:53], v[52:53], 1.0 op_sel_hi:[1,0]
	v_pk_add_f32 v[54:55], v[54:55], 1.0 op_sel_hi:[1,0]
	v_rcp_f32_e32 v60, v60
	v_rcp_f32_e32 v61, v61
	v_rcp_f32_e32 v62, v62
	v_rcp_f32_e32 v63, v63
	v_rcp_f32_e32 v52, v52
	v_rcp_f32_e32 v53, v53
	v_rcp_f32_e32 v54, v54
	v_rcp_f32_e32 v55, v55
	v_pk_mul_f32 v[60:61], v[158:159], v[60:61]
	v_pk_mul_f32 v[62:63], v[160:161], v[62:63]
	v_pk_mul_f32 v[52:53], v[158:159], v[52:53]
	v_pk_mul_f32 v[54:55], v[160:161], v[54:55]
	v_pk_mul_f32 v[56:57], v[56:57], v[60:61]
	v_pk_mul_f32 v[58:59], v[58:59], v[62:63]
	v_pk_mul_f32 v[48:49], v[48:49], v[52:53]
	v_pk_mul_f32 v[50:51], v[50:51], v[54:55]
	ds_write2_b32 v143, v56, v48 offset1:16
	ds_write2_b32 v143, v57, v49 offset0:36 offset1:52
	ds_write2_b32 v143, v58, v50 offset0:72 offset1:88
	ds_write2_b32 v143, v59, v51 offset0:108 offset1:124
	ds_read_b128 v[166:169], v141
	ds_read_b128 v[170:173], v141 offset:16
	ds_read_b128 v[150:153], v142 offset:640
	s_waitcnt lgkmcnt(7)
; __device__ __forceinline__ unsigned pack2(float lo, float hi) { unsigned r; asm volatile("v_cvt_pk_bf16_f32 %0, %1, %2" : "=v"(r) : "v"(lo), "v"(hi)); return r; }
; template <int EPI>
; __device__ __forceinline__ void gemm_phase(const GemmDesc d, u16* shm, unsigned sx, unsigned srank, unsigned snloc) {
;     ...
;           for (int m = 0; m < 4; ++m) {
;             const f32x4 r4 = *(const f32x4*)&lr[ai * 128 + wr2 * 64 + m * 16 + fq2 * 4];
;             const f32x4 rc4 = r4 * (-1.4426950408889634f), rr4 = r4 * r4;
; #pragma unroll
;             for (int n = 0; n < 2; ++n)
; #pragma unroll
;               for (int jp = 0; jp < 4; jp += 2) {
;                 const f32x2 a = {acc[ai][0][m][n][jp], acc[ai][0][m][n][jp + 1]}, b = {acc[ai][1][m][n][jp], acc[ai][1][m][n][jp + 1]};
;                 const f32x2 rc = {rc4[jp], rc4[jp + 1]}, rr = {rr4[jp], rr4[jp + 1]};
;                 const f32x2 tl = a * rc;
;                 f32x2 dd = {__builtin_amdgcn_exp2f(tl[0]), __builtin_amdgcn_exp2f(tl[1])};
;                 dd = dd + 1.0f;
;                 const f32x2 s = {__builtin_amdgcn_rcpf(dd[0]), __builtin_amdgcn_rcpf(dd[1])};
;                 const f32x2 o = (a * b) * (rr * s);
;                 stg[(fq2 * 4 + jp) * 36 + n * 16 + fr2] = o[0];
;                 stg[(fq2 * 4 + jp + 1) * 36 + n * 16 + fr2] = o[1];
;               }
;             {
;               const f32x4 v0 = *(const f32x4*)&stg[sw_row * 36 + sw_c8], v1 = *(const f32x4*)&stg[sw_row * 36 + sw_c8 + 4];
;               u32x4 w = {pack2(v0[0], v0[1]), pack2(v0[2], v0[3]), pack2(v1[0], v1[1]), pack2(v1[2], v1[3])};
;               __builtin_nontemporal_store(w, (u32x4*)(sw_base + (size_t)ai * (44 * 8192) + m * 1024));
;             }
;     ...
;       if constexpr (NEED_R) {
;         if (has_next && t2 < 256) lds_r[((it + 1) & 1) * 256 + t2] = R_ZERO(pnn, t2) ? 0.f : rsqrtf(ssn * (1.0f / DM) + EPS);
;       }
	v_pk_mul_f32 v[162:163], v[154:155], v[154:155]
	v_pk_mul_f32 v[164:165], v[156:157], v[156:157]
	v_pk_mul_f32 v[154:155], v[154:155], s[86:87] op_sel_hi:[1,0]
	v_pk_mul_f32 v[156:157], v[156:157], s[86:87] op_sel_hi:[1,0]
	v_pk_mul_f32 v[44:45], v[44:45], v[154:155]
	v_pk_mul_f32 v[46:47], v[46:47], v[156:157]
	v_pk_mul_f32 v[36:37], v[36:37], v[154:155]
	v_pk_mul_f32 v[38:39], v[38:39], v[156:157]
	v_exp_f32_e32 v44, v44
	v_exp_f32_e32 v45, v45
	v_exp_f32_e32 v46, v46
	v_exp_f32_e32 v47, v47
	v_exp_f32_e32 v36, v36
	v_exp_f32_e32 v37, v37
	v_exp_f32_e32 v38, v38
	v_exp_f32_e32 v39, v39
	v_pk_mul_f32 v[24:25], v[28:29], v[24:25]
	v_pk_mul_f32 v[26:27], v[30:31], v[26:27]
	v_pk_mul_f32 v[16:17], v[20:21], v[16:17]
	v_pk_mul_f32 v[18:19], v[22:23], v[18:19]
	s_waitcnt lgkmcnt(1)
	v_cvt_pk_bf16_f32 v166, v166, v167
	v_cvt_pk_bf16_f32 v167, v168, v169
	v_cvt_pk_bf16_f32 v168, v170, v171
	v_cvt_pk_bf16_f32 v169, v172, v173
	global_store_dwordx4 v[146:147], v[166:169], off nt
	v_pk_add_f32 v[44:45], v[44:45], 1.0 op_sel_hi:[1,0]
	v_pk_add_f32 v[46:47], v[46:47], 1.0 op_sel_hi:[1,0]
	v_pk_add_f32 v[36:37], v[36:37], 1.0 op_sel_hi:[1,0]
	v_pk_add_f32 v[38:39], v[38:39], 1.0 op_sel_hi:[1,0]
	v_rcp_f32_e32 v44, v44
	v_rcp_f32_e32 v45, v45
	v_rcp_f32_e32 v46, v46
	v_rcp_f32_e32 v47, v47
	v_rcp_f32_e32 v36, v36
	v_rcp_f32_e32 v37, v37
	v_rcp_f32_e32 v38, v38
	v_rcp_f32_e32 v39, v39
	v_pk_mul_f32 v[44:45], v[162:163], v[44:45]
	v_pk_mul_f32 v[46:47], v[164:165], v[46:47]
	v_pk_mul_f32 v[36:37], v[162:163], v[36:37]
	v_pk_mul_f32 v[38:39], v[164:165], v[38:39]
	v_pk_mul_f32 v[40:41], v[40:41], v[44:45]
	v_pk_mul_f32 v[42:43], v[42:43], v[46:47]
	v_pk_mul_f32 v[32:33], v[32:33], v[36:37]
	v_pk_mul_f32 v[34:35], v[34:35], v[38:39]
	ds_write2_b32 v143, v40, v32 offset1:16
	ds_write2_b32 v143, v41, v33 offset0:36 offset1:52
	ds_write2_b32 v143, v42, v34 offset0:72 offset1:88
	ds_write2_b32 v143, v43, v35 offset0:108 offset1:124
	ds_read_b128 v[190:193], v141
	ds_read_b128 v[194:197], v141 offset:16
	ds_read_b128 v[154:157], v142 offset:704
	s_waitcnt lgkmcnt(7)
	v_pk_mul_f32 v[158:159], v[150:151], v[150:151]
	v_pk_mul_f32 v[160:161], v[152:153], v[152:153]
	v_pk_mul_f32 v[150:151], v[150:151], s[86:87] op_sel_hi:[1,0]
	v_pk_mul_f32 v[152:153], v[152:153], s[86:87] op_sel_hi:[1,0]
	v_pk_mul_f32 v[28:29], v[28:29], v[150:151]
	v_pk_mul_f32 v[30:31], v[30:31], v[152:153]
	v_pk_mul_f32 v[20:21], v[20:21], v[150:151]
	v_pk_mul_f32 v[22:23], v[22:23], v[152:153]
	v_exp_f32_e32 v28, v28
	v_exp_f32_e32 v29, v29
	v_exp_f32_e32 v30, v30
	v_exp_f32_e32 v31, v31
	v_exp_f32_e32 v20, v20
	v_exp_f32_e32 v21, v21
	v_exp_f32_e32 v22, v22
	v_exp_f32_e32 v23, v23
	v_pk_mul_f32 v[8:9], v[12:13], v[8:9]
	v_pk_mul_f32 v[10:11], v[14:15], v[10:11]
	v_pk_mul_f32 v[0:1], v[4:5], v[0:1]
	v_pk_mul_f32 v[2:3], v[6:7], v[2:3]
	s_waitcnt lgkmcnt(1)
	v_cvt_pk_bf16_f32 v190, v190, v191
	v_cvt_pk_bf16_f32 v191, v192, v193
	v_cvt_pk_bf16_f32 v192, v194, v195
	v_cvt_pk_bf16_f32 v193, v196, v197
	global_store_dwordx4 v[146:147], v[190:193], off offset:2048 nt
	v_pk_add_f32 v[28:29], v[28:29], 1.0 op_sel_hi:[1,0]
	v_pk_add_f32 v[30:31], v[30:31], 1.0 op_sel_hi:[1,0]
	v_pk_add_f32 v[20:21], v[20:21], 1.0 op_sel_hi:[1,0]
	v_pk_add_f32 v[22:23], v[22:23], 1.0 op_sel_hi:[1,0]
	v_rcp_f32_e32 v28, v28
	v_rcp_f32_e32 v29, v29
	v_rcp_f32_e32 v30, v30
	v_rcp_f32_e32 v31, v31
	v_rcp_f32_e32 v20, v20
	v_rcp_f32_e32 v21, v21
	v_rcp_f32_e32 v22, v22
	v_rcp_f32_e32 v23, v23
	v_pk_mul_f32 v[28:29], v[158:159], v[28:29]
	v_pk_mul_f32 v[30:31], v[160:161], v[30:31]
	v_pk_mul_f32 v[20:21], v[158:159], v[20:21]
	v_pk_mul_f32 v[22:23], v[160:161], v[22:23]
	v_pk_mul_f32 v[24:25], v[24:25], v[28:29]
	v_pk_mul_f32 v[26:27], v[26:27], v[30:31]
	v_pk_mul_f32 v[16:17], v[16:17], v[20:21]
	v_pk_mul_f32 v[18:19], v[18:19], v[22:23]
	ds_write2_b32 v143, v24, v16 offset1:16
	ds_write2_b32 v143, v25, v17 offset0:36 offset1:52
	ds_write2_b32 v143, v26, v18 offset0:72 offset1:88
	ds_write2_b32 v143, v27, v19 offset0:108 offset1:124
	ds_read_b128 v[166:169], v141
	ds_read_b128 v[170:173], v141 offset:16
	s_waitcnt lgkmcnt(6)
	v_pk_mul_f32 v[162:163], v[154:155], v[154:155]
	v_pk_mul_f32 v[164:165], v[156:157], v[156:157]
	v_pk_mul_f32 v[154:155], v[154:155], s[86:87] op_sel_hi:[1,0]
	v_pk_mul_f32 v[156:157], v[156:157], s[86:87] op_sel_hi:[1,0]
	v_pk_mul_f32 v[12:13], v[12:13], v[154:155]
	v_pk_mul_f32 v[14:15], v[14:15], v[156:157]
	v_pk_mul_f32 v[4:5], v[4:5], v[154:155]
	v_pk_mul_f32 v[6:7], v[6:7], v[156:157]
	v_exp_f32_e32 v12, v12
	v_exp_f32_e32 v13, v13
	v_exp_f32_e32 v14, v14
	v_exp_f32_e32 v15, v15
	v_exp_f32_e32 v4, v4
	v_exp_f32_e32 v5, v5
	v_exp_f32_e32 v6, v6
	v_exp_f32_e32 v7, v7
	s_waitcnt lgkmcnt(0)
	v_cvt_pk_bf16_f32 v166, v166, v167
	v_cvt_pk_bf16_f32 v167, v168, v169
	v_cvt_pk_bf16_f32 v168, v170, v171
	v_cvt_pk_bf16_f32 v169, v172, v173
	global_store_dwordx4 v[148:149], v[166:169], off nt
	v_pk_add_f32 v[12:13], v[12:13], 1.0 op_sel_hi:[1,0]
	v_pk_add_f32 v[14:15], v[14:15], 1.0 op_sel_hi:[1,0]
	v_pk_add_f32 v[4:5], v[4:5], 1.0 op_sel_hi:[1,0]
	v_pk_add_f32 v[6:7], v[6:7], 1.0 op_sel_hi:[1,0]
	v_rcp_f32_e32 v12, v12
	v_rcp_f32_e32 v13, v13
	v_rcp_f32_e32 v14, v14
	v_rcp_f32_e32 v15, v15
	v_rcp_f32_e32 v4, v4
	v_rcp_f32_e32 v5, v5
	v_rcp_f32_e32 v6, v6
	v_rcp_f32_e32 v7, v7
	v_pk_mul_f32 v[12:13], v[162:163], v[12:13]
	v_pk_mul_f32 v[14:15], v[164:165], v[14:15]
	v_pk_mul_f32 v[4:5], v[162:163], v[4:5]
	v_pk_mul_f32 v[6:7], v[164:165], v[6:7]
	v_pk_mul_f32 v[8:9], v[8:9], v[12:13]
	v_pk_mul_f32 v[10:11], v[10:11], v[14:15]
	v_pk_mul_f32 v[0:1], v[0:1], v[4:5]
	v_pk_mul_f32 v[2:3], v[2:3], v[6:7]
	ds_write2_b32 v143, v8, v0 offset1:16
	ds_write2_b32 v143, v9, v1 offset0:36 offset1:52
	ds_write2_b32 v143, v10, v2 offset0:72 offset1:88
	ds_write2_b32 v143, v11, v3 offset0:108 offset1:124
	ds_read_b128 v[190:193], v141
	ds_read_b128 v[194:197], v141 offset:16
	s_waitcnt lgkmcnt(0)
	v_cvt_pk_bf16_f32 v190, v190, v191
	v_cvt_pk_bf16_f32 v191, v192, v193
	v_cvt_pk_bf16_f32 v192, v194, v195
	v_cvt_pk_bf16_f32 v193, v196, v197
	global_store_dwordx4 v[148:149], v[190:193], off offset:2048 nt
	s_and_saveexec_b64 s[4:5], s[34:35]
	s_cbranch_execz .LBB0_1454
	v_cmp_gt_f32_e32 vcc, s31, v140
	v_mul_f32_e32 v0, 0x4b800000, v140
	s_xor_b32 s0, s18, 0x100
	v_cndmask_b32_e32 v0, v140, v0, vcc
	v_rsq_f32_e32 v0, v0
	s_lshl_b32 s0, s0, 2
	s_add_i32 s0, s0, 0
	v_mul_f32_e32 v1, 0x45800000, v0
	v_cndmask_b32_e32 v0, v0, v1, vcc
	v_lshl_add_u32 v1, v139, 2, s0
	v_add_u32_e32 v1, 0x20000, v1
	ds_write_b32 v1, v0
